# speedup vs baseline: 1.0035x; 1.0035x over previous
; template <int MASK>
; __global__ void __launch_bounds__(256, 2) fwd_megakernel_t(Params p) {
;     ...
; #pragma unroll
;           for (int k = 0; k < 16; k++) {
;             float bv = -3e38f;
;             int bi = 0, bj = 0;
; #pragma unroll
;             for (int i = 0; i <= k; i++) {
;               const int j = (int)((P >> (4 * i)) & 15ull);
;               const float cnd = sv0[i] + l1v[j];
;               if (!((E >> i) & 1u) && cnd > bv) { bv = cnd; bi = i; bj = j; }
;             }
;             best[k] = bv;
;             pidx[ob + k] = li[row * 17 + bi] * 128 + li[(128 + row) * 17 + bj];
;             if (bj == 15) E |= 1u << bi; else P += 1ull << (4 * bi);
.LBB0_84:
	s_or_b64 exec, exec, s[72:73]
	v_add_f32_e32 v18, v16, v18
	v_cndmask_b32_e64 v51, v51, v52, s[16:17]
	v_cndmask_b32_e64 v47, v47, v48, s[14:15]
	v_cndmask_b32_e64 v42, v42, v43, s[12:13]
	v_cndmask_b32_e64 v38, v38, v39, s[10:11]
	v_max_f32_e32 v39, 0xff61b1e6, v18
	v_cndmask_b32_e32 v18, v19, v24, vcc
	v_cndmask_b32_e64 v19, v28, v29, s[6:7]
	v_cndmask_b32_e64 v24, v31, v32, s[8:9]
	v_lshl_add_u32 v28, v25, 2, v117
	v_lshl_add_u32 v29, v26, 2, v117
	v_lshl_add_u32 v31, v27, 2, v117
	v_lshl_add_u32 v32, v30, 2, v117
	v_lshl_add_u32 v43, v37, 2, v117
	v_lshl_add_u32 v48, v41, 2, v117
	v_lshl_add_u32 v52, v54, 2, v117
	v_cndmask_b32_e64 v55, v55, v56, s[18:19]
	ds_read_b32 v28, v28 offset:8704
	ds_read_b32 v29, v29 offset:8704
	ds_read_b32 v31, v31 offset:8704
	ds_read_b32 v32, v32 offset:8704
	ds_read_b32 v43, v43 offset:8704
	ds_read_b32 v48, v48 offset:8704
	ds_read_b32 v52, v52 offset:8704
	ds_read_b32 v56, v117 offset:8704
	s_waitcnt lgkmcnt(7)
	v_add_f32_e32 v16, v16, v28
	v_cmp_eq_u32_e32 vcc, 0, v33
	v_cmp_lt_f32_e64 s[6:7], s43, v16
	s_and_b64 vcc, vcc, s[6:7]
	v_cndmask_b32_e32 v16, v178, v16, vcc
	s_waitcnt lgkmcnt(6)
	v_add_f32_e32 v17, v17, v29
	v_cndmask_b32_e32 v25, 0, v25, vcc
	v_cmp_eq_u32_e32 vcc, 0, v34
	v_cmp_gt_f32_e64 s[6:7], v17, v16
	s_and_b64 vcc, vcc, s[6:7]
	v_cndmask_b32_e32 v16, v16, v17, vcc
	s_waitcnt lgkmcnt(5)
	v_add_f32_e32 v14, v14, v31
	v_cndmask_b32_e64 v17, 0, 1, vcc
	v_cndmask_b32_e32 v25, v25, v26, vcc
	v_cmp_eq_u32_e32 vcc, 0, v36
	v_cmp_gt_f32_e64 s[6:7], v14, v16
	s_and_b64 vcc, vcc, s[6:7]
	v_cndmask_b32_e32 v14, v16, v14, vcc
	s_waitcnt lgkmcnt(4)
	v_add_f32_e32 v15, v15, v32
	v_cndmask_b32_e64 v16, v17, 2, vcc
	v_cndmask_b32_e32 v17, v25, v27, vcc
	v_cmp_eq_u32_e32 vcc, 0, v35
	v_cmp_gt_f32_e64 s[6:7], v15, v14
	s_and_b64 vcc, vcc, s[6:7]
	v_cndmask_b32_e32 v14, v14, v15, vcc
	s_waitcnt lgkmcnt(3)
	v_add_f32_e32 v12, v12, v43
	v_cndmask_b32_e64 v15, v16, 3, vcc
	v_cndmask_b32_e32 v16, v17, v30, vcc
	v_cmp_eq_u32_e32 vcc, 0, v40
	v_cmp_gt_f32_e64 s[6:7], v12, v14
	s_and_b64 vcc, vcc, s[6:7]
	v_cndmask_b32_e32 v12, v14, v12, vcc
	s_waitcnt lgkmcnt(2)
	v_add_f32_e32 v13, v13, v48
	v_cndmask_b32_e64 v14, v15, 4, vcc
	v_cndmask_b32_e32 v15, v16, v37, vcc
	v_cmp_eq_u32_e32 vcc, 0, v44
	v_cmp_gt_f32_e64 s[6:7], v13, v12
	s_and_b64 vcc, vcc, s[6:7]
	v_cndmask_b32_e32 v12, v12, v13, vcc
	v_cndmask_b32_e64 v13, v14, 5, vcc
	v_cndmask_b32_e32 v14, v15, v41, vcc
	v_cmp_eq_u32_e32 vcc, 0, v49
	v_cmp_gt_f32_e64 s[6:7], v124, v12
	s_and_b64 vcc, vcc, s[6:7]
	v_cndmask_b32_e32 v12, v12, v124, vcc
	v_cndmask_b32_e64 v13, v13, 6, vcc
	v_cndmask_b32_e32 v14, v14, v46, vcc
	v_cmp_eq_u32_e32 vcc, 0, v53
	v_cmp_gt_f32_e64 s[6:7], v125, v12
	s_and_b64 vcc, vcc, s[6:7]
	v_cndmask_b32_e32 v12, v12, v125, vcc
	s_waitcnt lgkmcnt(1)
	v_add_f32_e32 v10, v10, v52
	v_cndmask_b32_e64 v13, v13, 7, vcc
	v_cndmask_b32_e32 v14, v14, v50, vcc
	v_cmp_eq_u32_e32 vcc, 0, v57
	v_cmp_gt_f32_e64 s[6:7], v10, v12
	s_and_b64 vcc, vcc, s[6:7]
	v_cndmask_b32_e32 v10, v12, v10, vcc
	v_cndmask_b32_e64 v12, v13, 8, vcc
	v_cndmask_b32_e32 v13, v14, v54, vcc
	v_lshl_add_u32 v14, v58, 2, v117
	v_lshl_add_u32 v15, v62, 2, v117
	v_lshl_add_u32 v16, v107, 2, v117
	v_lshl_add_u32 v17, v111, 2, v117
	v_lshl_add_u32 v25, v121, 2, v117
	v_lshl_add_u32 v26, v127, 2, v117
	ds_read_b32 v14, v14 offset:8704
	ds_read_b32 v15, v15 offset:8704
	ds_read_b32 v16, v16 offset:8704
	ds_read_b32 v17, v17 offset:8704
	ds_read_b32 v25, v25 offset:8704
	ds_read_b32 v26, v26 offset:8704
	s_waitcnt lgkmcnt(5)
	v_add_f32_e32 v11, v11, v14
	v_cmp_eq_u32_e32 vcc, 0, v59
	v_cmp_gt_f32_e64 s[6:7], v11, v10
	s_and_b64 vcc, vcc, s[6:7]
	v_cndmask_b32_e32 v10, v10, v11, vcc
	s_waitcnt lgkmcnt(4)
	v_add_f32_e32 v8, v8, v15
	v_cndmask_b32_e64 v11, v12, 9, vcc
	v_cndmask_b32_e32 v12, v13, v58, vcc
	v_cmp_eq_u32_e32 vcc, 0, v105
	v_cmp_gt_f32_e64 s[6:7], v8, v10
	s_and_b64 vcc, vcc, s[6:7]
	v_cndmask_b32_e32 v8, v10, v8, vcc
	s_waitcnt lgkmcnt(3)
	v_add_f32_e32 v9, v9, v16
	v_cndmask_b32_e64 v10, v11, 10, vcc
	v_cndmask_b32_e32 v11, v12, v62, vcc
	v_cmp_eq_u32_e32 vcc, 0, v109
	v_cmp_gt_f32_e64 s[6:7], v9, v8
	s_and_b64 vcc, vcc, s[6:7]
	v_cndmask_b32_e32 v8, v8, v9, vcc
	s_waitcnt lgkmcnt(2)
	v_add_f32_e32 v6, v6, v17
	v_cndmask_b32_e64 v9, v10, 11, vcc
	v_cndmask_b32_e32 v10, v11, v107, vcc
	v_cmp_eq_u32_e32 vcc, 0, v119
	v_cmp_gt_f32_e64 s[6:7], v6, v8
	s_and_b64 vcc, vcc, s[6:7]
	v_cndmask_b32_e32 v6, v8, v6, vcc
	s_waitcnt lgkmcnt(1)
; template <int MASK>
; __global__ void __launch_bounds__(256, 2) fwd_megakernel_t(Params p) {
;     ...
;           for (int k = 0; k < 16; k++) {
;             float bv = -3e38f;
;             int bi = 0, bj = 0;
; #pragma unroll
;             for (int i = 0; i <= k; i++) {
;               const int j = (int)((P >> (4 * i)) & 15ull);
;               const float cnd = sv0[i] + l1v[j];
;               if (!((E >> i) & 1u) && cnd > bv) { bv = cnd; bi = i; bj = j; }
;             }
;             best[k] = bv;
;             pidx[ob + k] = li[row * 17 + bi] * 128 + li[(128 + row) * 17 + bj];
;             if (bj == 15) E |= 1u << bi; else P += 1ull << (4 * bi);
;           }
;           const float b0 = best[0];
;           float sum = 0.f;
; #pragma unroll
;           for (int k = 0; k < 16; k++) { best[k] = __expf(best[k] - b0); sum += best[k]; }
;           const float isum = 1.f / sum;
; #pragma unroll
;           for (int k = 0; k < 16; k++) pgate[ob + k] = best[k] * isum;
	v_add_f32_e32 v7, v7, v25
	v_cndmask_b32_e64 v8, v9, 12, vcc
	v_cndmask_b32_e32 v9, v10, v111, vcc
	v_cmp_eq_u32_e32 vcc, 0, v122
	v_cmp_gt_f32_e64 s[6:7], v7, v6
	s_and_b64 vcc, vcc, s[6:7]
	v_cndmask_b32_e32 v6, v6, v7, vcc
	s_waitcnt lgkmcnt(0)
	v_add_f32_e32 v4, v4, v26
	v_cndmask_b32_e64 v7, v8, 13, vcc
	v_cndmask_b32_e32 v8, v9, v121, vcc
	v_cmp_gt_f32_e32 vcc, v4, v6
	s_and_b64 vcc, s[34:35], vcc
	v_add_f32_e32 v5, v5, v56
	v_cndmask_b32_e32 v4, v6, v4, vcc
	v_cndmask_b32_e64 v6, v7, 14, vcc
	v_cndmask_b32_e32 v7, v8, v127, vcc
	v_cmp_gt_f32_e32 vcc, v5, v4
	v_sub_f32_e32 v9, v42, v39
	v_mul_f32_e32 v9, 0x3fb8aa3b, v9
	v_cndmask_b32_e32 v25, v4, v5, vcc
	v_cndmask_b32_e64 v4, v6, 15, vcc
	v_cndmask_b32_e64 v5, v7, 0, vcc
	v_lshl_add_u32 v4, v4, 2, v117
	v_lshl_add_u32 v5, v5, 2, v117
	ds_read_b32 v26, v4 offset:17408
	ds_read_b32 v27, v5 offset:26112
	v_sub_f32_e32 v4, v39, v39
	v_mul_f32_e32 v4, 0x3fb8aa3b, v4
	v_sub_f32_e32 v5, v18, v39
	v_exp_f32_e32 v4, v4
	v_mul_f32_e32 v5, 0x3fb8aa3b, v5
	v_sub_f32_e32 v6, v19, v39
	v_exp_f32_e32 v5, v5
	v_mul_f32_e32 v6, 0x3fb8aa3b, v6
	v_sub_f32_e32 v7, v24, v39
	v_exp_f32_e32 v6, v6
	v_mul_f32_e32 v7, 0x3fb8aa3b, v7
	v_exp_f32_e32 v7, v7
	v_add_f32_e32 v8, 0, v4
	v_add_f32_e32 v8, v8, v5
	v_add_f32_e32 v8, v8, v6
	v_add_f32_e32 v12, v8, v7
	v_sub_f32_e32 v8, v38, v39
	v_mul_f32_e32 v8, 0x3fb8aa3b, v8
	v_exp_f32_e32 v8, v8
	v_sub_f32_e32 v10, v47, v39
	v_exp_f32_e32 v9, v9
	v_mul_f32_e32 v10, 0x3fb8aa3b, v10
	v_sub_f32_e32 v11, v51, v39
	v_exp_f32_e32 v10, v10
	v_mul_f32_e32 v11, 0x3fb8aa3b, v11
	v_exp_f32_e32 v11, v11
	v_add_f32_e32 v12, v12, v8
	v_add_f32_e32 v12, v12, v9
	v_add_f32_e32 v12, v12, v10
	v_cndmask_b32_e64 v60, v60, v61, s[20:21]
	v_add_f32_e32 v16, v12, v11
	v_sub_f32_e32 v12, v55, v39
	v_cndmask_b32_e64 v45, v63, v104, s[22:23]
	v_mul_f32_e32 v12, 0x3fb8aa3b, v12
	v_sub_f32_e32 v13, v60, v39
	v_cndmask_b32_e64 v23, v106, v108, s[24:25]
	v_exp_f32_e32 v12, v12
	v_mul_f32_e32 v13, 0x3fb8aa3b, v13
	v_sub_f32_e32 v14, v45, v39
	v_exp_f32_e32 v13, v13
	v_mul_f32_e32 v14, 0x3fb8aa3b, v14
	v_sub_f32_e32 v15, v23, v39
	v_exp_f32_e32 v14, v14
	v_mul_f32_e32 v15, 0x3fb8aa3b, v15
	v_exp_f32_e32 v15, v15
	v_add_f32_e32 v16, v16, v12
	v_add_f32_e32 v16, v16, v13
	v_cndmask_b32_e64 v22, v110, v118, s[26:27]
	v_add_f32_e32 v16, v16, v14
	v_cndmask_b32_e64 v21, v120, v123, s[28:29]
	v_add_f32_e32 v23, v16, v15
	v_sub_f32_e32 v16, v22, v39
	v_cndmask_b32_e64 v20, v126, v129, s[30:31]
	v_mul_f32_e32 v16, 0x3fb8aa3b, v16
	v_sub_f32_e32 v17, v21, v39
	v_exp_f32_e32 v16, v16
	v_mul_f32_e32 v17, 0x3fb8aa3b, v17
	v_sub_f32_e32 v18, v20, v39
	v_exp_f32_e32 v17, v17
	v_mul_f32_e32 v18, 0x3fb8aa3b, v18
	v_sub_f32_e32 v19, v25, v39
	v_exp_f32_e32 v18, v18
	v_mul_f32_e32 v19, 0x3fb8aa3b, v19
	v_exp_f32_e32 v19, v19
	v_add_f32_e32 v20, v23, v16
	v_add_f32_e32 v20, v20, v17
	v_add_f32_e32 v20, v20, v18
	v_add_f32_e32 v20, v20, v19
	v_div_scale_f32 v21, s[6:7], v20, v20, 1.0
	v_rcp_f32_e32 v22, v21
	s_waitcnt lgkmcnt(0)
	v_lshl_add_u32 v23, v26, 7, v27
	v_mov_b32_e32 v231, v23
	global_store_dwordx4 v[2:3], v[220:223], off offset:16
	global_store_dwordx4 v[2:3], v[224:227], off offset:32
	global_store_dwordx4 v[2:3], v[228:231], off offset:48
	v_readlane_b32 s6, v255, 51
	v_fma_f32 v2, -v21, v22, 1.0
	v_fmac_f32_e32 v22, v2, v22
	v_div_scale_f32 v2, vcc, 1.0, v20, 1.0
	v_mul_f32_e32 v3, v2, v22
	v_fma_f32 v23, -v21, v3, v2
	v_fmac_f32_e32 v3, v23, v22
	v_fma_f32 v2, -v21, v3, v2
	v_div_fmas_f32 v2, v2, v22, v3
	v_lshlrev_b64 v[0:1], 4, v[0:1]
	v_div_fixup_f32 v20, v2, v20, 1.0
	v_readlane_b32 s7, v255, 52
	v_pk_mul_f32 v[2:3], v[20:21], v[6:7] op_sel_hi:[0,1]
	s_nop 0
	v_lshl_add_u64 v[22:23], v[0:1], 2, s[6:7]
	v_pk_mul_f32 v[0:1], v[20:21], v[4:5] op_sel_hi:[0,1]
	global_store_dwordx4 v[22:23], v[0:3], off
	s_nop 1
	v_pk_mul_f32 v[0:1], v[20:21], v[8:9] op_sel_hi:[0,1]
	v_pk_mul_f32 v[2:3], v[20:21], v[10:11] op_sel_hi:[0,1]
	global_store_dwordx4 v[22:23], v[0:3], off offset:16
	s_nop 1
	v_pk_mul_f32 v[0:1], v[20:21], v[12:13] op_sel_hi:[0,1]
	v_pk_mul_f32 v[2:3], v[20:21], v[14:15] op_sel_hi:[0,1]
	global_store_dwordx4 v[22:23], v[0:3], off offset:32
	s_nop 1
	v_pk_mul_f32 v[0:1], v[20:21], v[16:17] op_sel_hi:[0,1]
	v_pk_mul_f32 v[2:3], v[20:21], v[18:19] op_sel_hi:[0,1]
	global_store_dwordx4 v[22:23], v[0:3], off offset:48

; template <int MASK>
; __global__ void __launch_bounds__(256, 2) fwd_megakernel_t(Params p) {
;     ...
;           for (int k = 0; k < 16; k++) {
;             float bv = -3e38f;
;             int bi = 0, bj = 0;
; #pragma unroll
;             for (int i = 0; i <= k; i++) {
;               const int j = (int)((P >> (4 * i)) & 15ull);
;               const float cnd = sv0[i] + l1v[j];
;               if (!((E >> i) & 1u) && cnd > bv) { bv = cnd; bi = i; bj = j; }
;             }
;             best[k] = bv;
;             pidx[ob + k] = li[row * 17 + bi] * 128 + li[(128 + row) * 17 + bj];
;             if (bj == 15) E |= 1u << bi; else P += 1ull << (4 * bi);
.LBB0_217:
	s_or_saveexec_b64 s[10:11], s[10:11]
	v_mov_b32_e32 v35, 0
	v_mov_b32_e32 v36, 0
	v_mov_b32_e32 v34, 0
	v_mov_b32_e32 v33, 0
	v_mov_b32_e32 v45, 0
	s_xor_b64 exec, exec, s[10:11]
	v_lshlrev_b32_e64 v45, v37, 1
	v_and_b32_e32 v33, 1, v45
	v_and_b32_e32 v34, 2, v45
	v_and_b32_e32 v36, 4, v45
	v_and_b32_e32 v35, 8, v45
	v_mov_b32_e32 v30, 0
	v_mov_b64_e32 v[22:23], v[150:151]
	s_or_b64 exec, exec, s[10:11]
	v_cmp_eq_u32_e64 s[10:11], 0, v33
	v_cmp_lt_f32_e64 s[12:13], s43, v50
	s_and_b64 s[10:11], s[10:11], s[12:13]
	v_cndmask_b32_e64 v37, v178, v50, s[10:11]
	v_lshl_add_u32 v40, v30, 2, v117
	v_cndmask_b32_e64 v38, 0, v25, s[10:11]
	v_cmp_eq_u32_e64 s[10:11], 0, v34
	v_cmp_gt_f32_e64 s[12:13], v51, v37
	ds_read_b32 v40, v40 offset:8704
	s_and_b64 s[10:11], s[10:11], s[12:13]
	v_cndmask_b32_e64 v37, v37, v51, s[10:11]
	v_cndmask_b32_e64 v39, 0, 1, s[10:11]
	v_cndmask_b32_e64 v38, v38, v26, s[10:11]
	v_cmp_eq_u32_e64 s[10:11], 0, v36
	v_cmp_gt_f32_e64 s[12:13], v52, v37
	ds_read_b32 v54, v117 offset:8704
	s_and_b64 s[10:11], s[10:11], s[12:13]
	v_cndmask_b32_e64 v37, v37, v52, s[10:11]
	s_waitcnt lgkmcnt(1)
	v_add_f32_e32 v53, v15, v40
	v_cndmask_b32_e64 v39, v39, 2, s[10:11]
	v_cndmask_b32_e64 v41, v38, v27, s[10:11]
	v_cmp_eq_u32_e64 s[10:11], 0, v35
	v_cmp_gt_f32_e64 s[12:13], v53, v37
	s_and_b64 s[10:11], s[10:11], s[12:13]
	v_cndmask_b32_e64 v38, v37, v53, s[10:11]
	v_cndmask_b32_e64 v37, v39, 3, s[10:11]
	s_waitcnt lgkmcnt(0)
	v_add_f32_e32 v39, v12, v54
	v_cndmask_b32_e64 v40, v41, v30, s[10:11]
	v_cmp_gt_f32_e64 s[10:11], v39, v38
	s_nop 1
	v_cndmask_b32_e64 v41, v37, 4, s[10:11]
	v_cndmask_b32_e64 v37, v40, 0, s[10:11]
	v_lshl_add_u32 v40, v41, 2, v117
	v_lshl_add_u32 v42, v37, 2, v117
	ds_read_b32 v40, v40 offset:17408
	ds_read_b32 v42, v42 offset:26112
	v_cmp_ne_u32_e64 s[12:13], 15, v37
	s_waitcnt lgkmcnt(0)
	v_lshl_add_u32 v40, v40, 7, v42
	v_mov_b32_e32 v220, v40
	s_and_saveexec_b64 s[14:15], s[12:13]
	s_xor_b64 s[12:13], exec, s[14:15]
	s_cbranch_execz .LBB0_221
	v_lshlrev_b32_e32 v25, 2, v41
	v_lshlrev_b64 v[26:27], v25, 1
	v_lshl_add_u64 v[22:23], v[26:27], 0, v[22:23]
	v_and_b32_e32 v25, 15, v22
	v_bfe_u32 v26, v22, 4, 4
	v_bfe_u32 v27, v22, 8, 4
	v_bfe_u32 v30, v22, 12, 4
	v_alignbit_b32 v37, v23, v22, 16
	v_lshl_add_u32 v40, v25, 2, v117
	v_lshl_add_u32 v41, v26, 2, v117
	v_lshl_add_u32 v42, v27, 2, v117
	v_lshl_add_u32 v43, v30, 2, v117
	v_lshl_add_u32 v44, v37, 2, v117
	ds_read_b32 v40, v40 offset:8704
	ds_read_b32 v41, v41 offset:8704
	ds_read_b32 v42, v42 offset:8704
	ds_read_b32 v43, v43 offset:8704
	ds_read_b32 v44, v44 offset:8704
	s_waitcnt lgkmcnt(4)
	v_add_f32_e32 v50, v16, v40
	s_waitcnt lgkmcnt(3)
	v_add_f32_e32 v51, v17, v41
	s_waitcnt lgkmcnt(2)
	v_add_f32_e32 v52, v14, v42
	s_waitcnt lgkmcnt(1)
	v_add_f32_e32 v53, v15, v43
	s_waitcnt lgkmcnt(0)
	v_add_f32_e32 v55, v12, v44

; template <int MASK>
; __global__ void __launch_bounds__(256, 2) fwd_megakernel_t(Params p) {
;     ...
;           for (int k = 0; k < 16; k++) {
;             float bv = -3e38f;
;             int bi = 0, bj = 0;
; #pragma unroll
;             for (int i = 0; i <= k; i++) {
;               const int j = (int)((P >> (4 * i)) & 15ull);
;               const float cnd = sv0[i] + l1v[j];
;               if (!((E >> i) & 1u) && cnd > bv) { bv = cnd; bi = i; bj = j; }
;             }
;             best[k] = bv;
;             pidx[ob + k] = li[row * 17 + bi] * 128 + li[(128 + row) * 17 + bj];
;             if (bj == 15) E |= 1u << bi; else P += 1ull << (4 * bi);
.LBB0_223:
	s_or_b64 exec, exec, s[12:13]
	v_cmp_eq_u32_e64 s[12:13], 0, v33
	v_cmp_lt_f32_e64 s[14:15], s43, v50
	s_and_b64 s[12:13], s[12:13], s[14:15]
	v_cndmask_b32_e64 v41, v178, v50, s[12:13]
	v_cndmask_b32_e64 v42, 0, v25, s[12:13]
	v_cmp_eq_u32_e64 s[12:13], 0, v34
	v_cmp_gt_f32_e64 s[14:15], v51, v41
	s_and_b64 s[12:13], s[12:13], s[14:15]
	v_cndmask_b32_e64 v41, v41, v51, s[12:13]
	v_cndmask_b32_e64 v43, 0, 1, s[12:13]
	v_cndmask_b32_e64 v42, v42, v26, s[12:13]
	v_cmp_eq_u32_e64 s[12:13], 0, v36
	v_cmp_gt_f32_e64 s[14:15], v52, v41
	s_and_b64 s[12:13], s[12:13], s[14:15]
	v_cndmask_b32_e64 v41, v41, v52, s[12:13]
	v_cndmask_b32_e64 v43, v43, 2, s[12:13]
	v_cndmask_b32_e64 v42, v42, v27, s[12:13]
	v_cmp_eq_u32_e64 s[12:13], 0, v35
	v_cmp_gt_f32_e64 s[14:15], v53, v41
	s_and_b64 s[12:13], s[12:13], s[14:15]
	v_cndmask_b32_e64 v41, v41, v53, s[12:13]
	v_cndmask_b32_e64 v43, v43, 3, s[12:13]
	v_cndmask_b32_e64 v44, v42, v30, s[12:13]
	v_cmp_eq_u32_e64 s[12:13], 0, v40
	v_cmp_gt_f32_e64 s[14:15], v55, v41
	s_and_b64 s[12:13], s[12:13], s[14:15]
	v_cndmask_b32_e64 v42, v41, v55, s[12:13]
	v_cndmask_b32_e64 v41, v43, 4, s[12:13]
	v_add_f32_e32 v43, v13, v54
	v_cndmask_b32_e64 v44, v44, v37, s[12:13]
	v_cmp_gt_f32_e64 s[12:13], v43, v42
	s_nop 1
	v_cndmask_b32_e64 v46, v41, 5, s[12:13]
	v_cndmask_b32_e64 v41, v44, 0, s[12:13]
	v_lshl_add_u32 v44, v46, 2, v117
	v_lshl_add_u32 v47, v41, 2, v117
	ds_read_b32 v44, v44 offset:17408
	ds_read_b32 v47, v47 offset:26112
	v_cmp_ne_u32_e64 s[14:15], 15, v41
	s_waitcnt lgkmcnt(0)
	v_lshl_add_u32 v44, v44, 7, v47
	v_mov_b32_e32 v221, v44
	s_and_saveexec_b64 s[16:17], s[14:15]
	s_xor_b64 s[14:15], exec, s[16:17]
	s_cbranch_execz .LBB0_225
	v_lshlrev_b32_e32 v25, 2, v46
	v_lshlrev_b64 v[26:27], v25, 1
	v_lshl_add_u64 v[22:23], v[26:27], 0, v[22:23]
	v_and_b32_e32 v25, 15, v22
	v_bfe_u32 v26, v22, 4, 4
	v_bfe_u32 v27, v22, 8, 4
	v_bfe_u32 v30, v22, 12, 4
	v_bfe_u32 v37, v22, 16, 4
	v_alignbit_b32 v41, v23, v22, 20
	v_lshl_add_u32 v44, v25, 2, v117
	v_lshl_add_u32 v46, v26, 2, v117
	v_lshl_add_u32 v47, v27, 2, v117
	v_lshl_add_u32 v48, v30, 2, v117
	v_lshl_add_u32 v49, v37, 2, v117
	v_lshl_add_u32 v50, v41, 2, v117
	ds_read_b32 v44, v44 offset:8704
	ds_read_b32 v46, v46 offset:8704
	ds_read_b32 v47, v47 offset:8704
	ds_read_b32 v48, v48 offset:8704
	ds_read_b32 v49, v49 offset:8704
	ds_read_b32 v56, v50 offset:8704
	s_waitcnt lgkmcnt(5)
	v_add_f32_e32 v50, v16, v44
	s_waitcnt lgkmcnt(4)
	v_add_f32_e32 v51, v17, v46
	s_waitcnt lgkmcnt(3)
	v_add_f32_e32 v52, v14, v47
	s_waitcnt lgkmcnt(2)
	v_add_f32_e32 v53, v15, v48
	s_waitcnt lgkmcnt(1)
	v_add_f32_e32 v55, v12, v49
	s_waitcnt lgkmcnt(0)
	v_add_f32_e32 v56, v13, v56

; template <int MASK>
; __global__ void __launch_bounds__(256, 2) fwd_megakernel_t(Params p) {
;     ...
;           for (int k = 0; k < 16; k++) {
;             float bv = -3e38f;
;             int bi = 0, bj = 0;
; #pragma unroll
;             for (int i = 0; i <= k; i++) {
;               const int j = (int)((P >> (4 * i)) & 15ull);
;               const float cnd = sv0[i] + l1v[j];
;               if (!((E >> i) & 1u) && cnd > bv) { bv = cnd; bi = i; bj = j; }
;             }
;             best[k] = bv;
;             pidx[ob + k] = li[row * 17 + bi] * 128 + li[(128 + row) * 17 + bj];
;             if (bj == 15) E |= 1u << bi; else P += 1ull << (4 * bi);
.LBB0_227:
	s_or_b64 exec, exec, s[14:15]
	v_cmp_eq_u32_e64 s[14:15], 0, v33
	v_cmp_lt_f32_e64 s[16:17], s43, v50
	s_and_b64 s[14:15], s[14:15], s[16:17]
	v_cndmask_b32_e64 v46, v178, v50, s[14:15]
	v_cndmask_b32_e64 v47, 0, v25, s[14:15]
	v_cmp_eq_u32_e64 s[14:15], 0, v34
	v_cmp_gt_f32_e64 s[16:17], v51, v46
	s_and_b64 s[14:15], s[14:15], s[16:17]
	v_cndmask_b32_e64 v46, v46, v51, s[14:15]
	v_cndmask_b32_e64 v48, 0, 1, s[14:15]
	v_cndmask_b32_e64 v47, v47, v26, s[14:15]
	v_cmp_eq_u32_e64 s[14:15], 0, v36
	v_cmp_gt_f32_e64 s[16:17], v52, v46
	s_and_b64 s[14:15], s[14:15], s[16:17]
	v_cndmask_b32_e64 v46, v46, v52, s[14:15]
	v_cndmask_b32_e64 v48, v48, 2, s[14:15]
	v_cndmask_b32_e64 v47, v47, v27, s[14:15]
	v_cmp_eq_u32_e64 s[14:15], 0, v35
	v_cmp_gt_f32_e64 s[16:17], v53, v46
	s_and_b64 s[14:15], s[14:15], s[16:17]
	v_cndmask_b32_e64 v46, v46, v53, s[14:15]
	v_cndmask_b32_e64 v48, v48, 3, s[14:15]
	v_cndmask_b32_e64 v47, v47, v30, s[14:15]
	v_cmp_eq_u32_e64 s[14:15], 0, v40
	v_cmp_gt_f32_e64 s[16:17], v55, v46
	s_and_b64 s[14:15], s[14:15], s[16:17]
	v_cndmask_b32_e64 v46, v46, v55, s[14:15]
	v_cndmask_b32_e64 v48, v48, 4, s[14:15]
	v_cndmask_b32_e64 v49, v47, v37, s[14:15]
	v_cmp_eq_u32_e64 s[14:15], 0, v44
	v_cmp_gt_f32_e64 s[16:17], v56, v46
	s_and_b64 s[14:15], s[14:15], s[16:17]
	v_cndmask_b32_e64 v47, v46, v56, s[14:15]
	v_cndmask_b32_e64 v46, v48, 5, s[14:15]
	v_add_f32_e32 v48, v20, v54
	v_cndmask_b32_e64 v49, v49, v41, s[14:15]
	v_cmp_gt_f32_e64 s[14:15], v48, v47
	s_nop 1
	v_cndmask_b32_e64 v58, v46, 6, s[14:15]
	v_cndmask_b32_e64 v46, v49, 0, s[14:15]
	v_lshl_add_u32 v49, v58, 2, v117
	v_lshl_add_u32 v57, v46, 2, v117
	ds_read_b32 v49, v49 offset:17408
	ds_read_b32 v57, v57 offset:26112
	v_cmp_ne_u32_e64 s[16:17], 15, v46
	s_waitcnt lgkmcnt(0)
	v_lshl_add_u32 v49, v49, 7, v57
	v_mov_b32_e32 v222, v49
	s_and_saveexec_b64 s[18:19], s[16:17]
	s_xor_b64 s[16:17], exec, s[18:19]
	s_cbranch_execz .LBB0_229
	v_lshlrev_b32_e32 v25, 2, v58
	v_lshlrev_b64 v[26:27], v25, 1
	v_lshl_add_u64 v[22:23], v[26:27], 0, v[22:23]
	v_and_b32_e32 v25, 15, v22
	v_bfe_u32 v26, v22, 4, 4
	v_bfe_u32 v27, v22, 8, 4
	v_bfe_u32 v30, v22, 12, 4
	v_bfe_u32 v37, v22, 16, 4
	v_bfe_u32 v41, v22, 20, 4
	v_alignbit_b32 v46, v23, v22, 24
	v_lshl_add_u32 v49, v25, 2, v117
	v_lshl_add_u32 v50, v26, 2, v117
	v_lshl_add_u32 v51, v27, 2, v117
	v_lshl_add_u32 v52, v30, 2, v117
	v_lshl_add_u32 v53, v37, 2, v117
	v_lshl_add_u32 v55, v41, 2, v117
	v_lshl_add_u32 v56, v46, 2, v117
	ds_read_b32 v49, v49 offset:8704
	ds_read_b32 v57, v50 offset:8704
	ds_read_b32 v58, v51 offset:8704
	ds_read_b32 v59, v52 offset:8704
	ds_read_b32 v60, v53 offset:8704
	ds_read_b32 v61, v55 offset:8704
	ds_read_b32 v62, v56 offset:8704
	s_waitcnt lgkmcnt(6)
	v_add_f32_e32 v50, v16, v49
	s_waitcnt lgkmcnt(5)
	v_add_f32_e32 v51, v17, v57
	s_waitcnt lgkmcnt(4)
	v_add_f32_e32 v52, v14, v58
	s_waitcnt lgkmcnt(3)
	v_add_f32_e32 v53, v15, v59
	s_waitcnt lgkmcnt(2)
	v_add_f32_e32 v55, v12, v60
	s_waitcnt lgkmcnt(1)
	v_add_f32_e32 v56, v13, v61
	s_waitcnt lgkmcnt(0)
	v_add_f32_e32 v57, v20, v62

; template <int MASK>
; __global__ void __launch_bounds__(256, 2) fwd_megakernel_t(Params p) {
;     ...
;           for (int k = 0; k < 16; k++) {
;             float bv = -3e38f;
;             int bi = 0, bj = 0;
; #pragma unroll
;             for (int i = 0; i <= k; i++) {
;               const int j = (int)((P >> (4 * i)) & 15ull);
;               const float cnd = sv0[i] + l1v[j];
;               if (!((E >> i) & 1u) && cnd > bv) { bv = cnd; bi = i; bj = j; }
;             }
;             best[k] = bv;
;             pidx[ob + k] = li[row * 17 + bi] * 128 + li[(128 + row) * 17 + bj];
;             if (bj == 15) E |= 1u << bi; else P += 1ull << (4 * bi);
.LBB0_231:
	s_or_b64 exec, exec, s[16:17]
	v_cmp_eq_u32_e64 s[16:17], 0, v33
	v_cmp_lt_f32_e64 s[18:19], s43, v50
	s_and_b64 s[16:17], s[16:17], s[18:19]
	v_cndmask_b32_e64 v50, v178, v50, s[16:17]
	v_cndmask_b32_e64 v58, 0, v25, s[16:17]
	v_cmp_eq_u32_e64 s[16:17], 0, v34
	v_cmp_gt_f32_e64 s[18:19], v51, v50
	s_and_b64 s[16:17], s[16:17], s[18:19]
	v_cndmask_b32_e64 v50, v50, v51, s[16:17]
	v_cndmask_b32_e64 v51, 0, 1, s[16:17]
	v_cndmask_b32_e64 v58, v58, v26, s[16:17]
	v_cmp_eq_u32_e64 s[16:17], 0, v36
	v_cmp_gt_f32_e64 s[18:19], v52, v50
	s_and_b64 s[16:17], s[16:17], s[18:19]
	v_cndmask_b32_e64 v50, v50, v52, s[16:17]
	v_cndmask_b32_e64 v51, v51, 2, s[16:17]
	v_cndmask_b32_e64 v52, v58, v27, s[16:17]
	v_cmp_eq_u32_e64 s[16:17], 0, v35
	v_cmp_gt_f32_e64 s[18:19], v53, v50
	s_and_b64 s[16:17], s[16:17], s[18:19]
	v_cndmask_b32_e64 v50, v50, v53, s[16:17]
	v_cndmask_b32_e64 v51, v51, 3, s[16:17]
	v_cndmask_b32_e64 v52, v52, v30, s[16:17]
	v_cmp_eq_u32_e64 s[16:17], 0, v40
	v_cmp_gt_f32_e64 s[18:19], v55, v50
	s_and_b64 s[16:17], s[16:17], s[18:19]
	v_cndmask_b32_e64 v50, v50, v55, s[16:17]
	v_cndmask_b32_e64 v51, v51, 4, s[16:17]
	v_cndmask_b32_e64 v52, v52, v37, s[16:17]
	v_cmp_eq_u32_e64 s[16:17], 0, v44
	v_cmp_gt_f32_e64 s[18:19], v56, v50
	s_and_b64 s[16:17], s[16:17], s[18:19]
	v_cndmask_b32_e64 v50, v50, v56, s[16:17]
	v_cndmask_b32_e64 v53, v51, 5, s[16:17]
	v_cndmask_b32_e64 v52, v52, v41, s[16:17]
	v_cmp_eq_u32_e64 s[16:17], 0, v49
	v_cmp_gt_f32_e64 s[18:19], v57, v50
	s_and_b64 s[16:17], s[16:17], s[18:19]
	v_cndmask_b32_e64 v51, v50, v57, s[16:17]
	v_cndmask_b32_e64 v50, v53, 6, s[16:17]
	v_cndmask_b32_e64 v53, v52, v46, s[16:17]
	v_add_f32_e32 v52, v21, v54
	v_cmp_gt_f32_e64 s[16:17], v52, v51
	s_nop 1
	v_cndmask_b32_e64 v55, v50, 7, s[16:17]
	v_cndmask_b32_e64 v50, v53, 0, s[16:17]
	v_lshl_add_u32 v53, v55, 2, v117
	v_lshl_add_u32 v56, v50, 2, v117
	ds_read_b32 v53, v53 offset:17408
	ds_read_b32 v56, v56 offset:26112
	v_cmp_ne_u32_e64 s[18:19], 15, v50
	s_waitcnt lgkmcnt(0)
	v_lshl_add_u32 v53, v53, 7, v56
	v_mov_b32_e32 v223, v53
	s_and_saveexec_b64 s[20:21], s[18:19]
	s_xor_b64 s[18:19], exec, s[20:21]
	s_cbranch_execz .LBB0_233
	v_lshlrev_b32_e32 v25, 2, v55
	v_lshlrev_b64 v[26:27], v25, 1
	v_lshl_add_u64 v[22:23], v[26:27], 0, v[22:23]
	v_alignbit_b32 v50, v23, v22, 28
	v_lshl_add_u32 v30, v50, 2, v117
	ds_read_b32 v53, v30 offset:8704
	v_and_b32_e32 v25, 15, v22
	v_bfe_u32 v26, v22, 4, 4
	v_bfe_u32 v27, v22, 8, 4
	v_bfe_u32 v30, v22, 12, 4
	v_bfe_u32 v37, v22, 16, 4
	v_bfe_u32 v41, v22, 20, 4
	v_bfe_u32 v46, v22, 24, 4
	s_waitcnt lgkmcnt(0)
	v_add_f32_e32 v58, v21, v53

; template <int MASK>
; __global__ void __launch_bounds__(256, 2) fwd_megakernel_t(Params p) {
;     ...
;           for (int k = 0; k < 16; k++) {
;             float bv = -3e38f;
;             int bi = 0, bj = 0;
; #pragma unroll
;             for (int i = 0; i <= k; i++) {
;               const int j = (int)((P >> (4 * i)) & 15ull);
;               const float cnd = sv0[i] + l1v[j];
;               if (!((E >> i) & 1u) && cnd > bv) { bv = cnd; bi = i; bj = j; }
;             }
;             best[k] = bv;
;             pidx[ob + k] = li[row * 17 + bi] * 128 + li[(128 + row) * 17 + bj];
;             if (bj == 15) E |= 1u << bi; else P += 1ull << (4 * bi);
.LBB0_235:
	s_or_b64 exec, exec, s[18:19]
	v_lshl_add_u32 v55, v25, 2, v117
	v_lshl_add_u32 v56, v26, 2, v117
	v_lshl_add_u32 v57, v27, 2, v117
	v_lshl_add_u32 v59, v30, 2, v117
	v_lshl_add_u32 v60, v37, 2, v117
	v_lshl_add_u32 v61, v41, 2, v117
	v_lshl_add_u32 v62, v46, 2, v117
	ds_read_b32 v55, v55 offset:8704
	ds_read_b32 v56, v56 offset:8704
	ds_read_b32 v57, v57 offset:8704
	ds_read_b32 v63, v59 offset:8704
	ds_read_b32 v70, v60 offset:8704
	ds_read_b32 v71, v61 offset:8704
	ds_read_b32 v72, v62 offset:8704
	s_waitcnt lgkmcnt(6)
	v_add_f32_e32 v59, v16, v55
	v_cmp_eq_u32_e64 s[18:19], 0, v33
	v_cmp_lt_f32_e64 s[20:21], s43, v59
	s_and_b64 s[18:19], s[18:19], s[20:21]
	v_cndmask_b32_e64 v55, v178, v59, s[18:19]
	s_waitcnt lgkmcnt(5)
	v_add_f32_e32 v60, v17, v56
	v_cndmask_b32_e64 v61, 0, v25, s[18:19]
	v_cmp_eq_u32_e64 s[18:19], 0, v34
	v_cmp_gt_f32_e64 s[20:21], v60, v55
	s_and_b64 s[18:19], s[18:19], s[20:21]
	v_cndmask_b32_e64 v55, v55, v60, s[18:19]
	v_cndmask_b32_e64 v62, v61, v26, s[18:19]
	s_waitcnt lgkmcnt(4)
	v_add_f32_e32 v61, v14, v57
	v_cndmask_b32_e64 v56, 0, 1, s[18:19]
	v_cmp_eq_u32_e64 s[18:19], 0, v36
	v_cmp_gt_f32_e64 s[20:21], v61, v55
	s_and_b64 s[18:19], s[18:19], s[20:21]
	v_cndmask_b32_e64 v55, v55, v61, s[18:19]
	v_cndmask_b32_e64 v57, v62, v27, s[18:19]
	s_waitcnt lgkmcnt(3)
	v_add_f32_e32 v62, v15, v63
	v_cndmask_b32_e64 v56, v56, 2, s[18:19]
	v_cmp_eq_u32_e64 s[18:19], 0, v35
	v_cmp_gt_f32_e64 s[20:21], v62, v55
	s_and_b64 s[18:19], s[18:19], s[20:21]
	v_cndmask_b32_e64 v55, v55, v62, s[18:19]
	s_waitcnt lgkmcnt(2)
	v_add_f32_e32 v63, v12, v70
	v_cndmask_b32_e64 v56, v56, 3, s[18:19]
	v_cndmask_b32_e64 v57, v57, v30, s[18:19]
	v_cmp_eq_u32_e64 s[18:19], 0, v40
	v_cmp_gt_f32_e64 s[20:21], v63, v55
	s_and_b64 s[18:19], s[18:19], s[20:21]
	v_cndmask_b32_e64 v55, v55, v63, s[18:19]
	s_waitcnt lgkmcnt(1)
	v_add_f32_e32 v104, v13, v71
	v_cndmask_b32_e64 v56, v56, 4, s[18:19]
	v_cndmask_b32_e64 v57, v57, v37, s[18:19]
	v_cmp_eq_u32_e64 s[18:19], 0, v44
	v_cmp_gt_f32_e64 s[20:21], v104, v55
	s_and_b64 s[18:19], s[18:19], s[20:21]
	v_cndmask_b32_e64 v55, v55, v104, s[18:19]
	s_waitcnt lgkmcnt(0)
	v_add_f32_e32 v105, v20, v72
	v_cndmask_b32_e64 v56, v56, 5, s[18:19]
	v_cndmask_b32_e64 v57, v57, v41, s[18:19]
	v_cmp_eq_u32_e64 s[18:19], 0, v49
	v_cmp_gt_f32_e64 s[20:21], v105, v55
	s_and_b64 s[18:19], s[18:19], s[20:21]
	v_cndmask_b32_e64 v55, v55, v105, s[18:19]
	v_cndmask_b32_e64 v56, v56, 6, s[18:19]
	v_cndmask_b32_e64 v57, v57, v46, s[18:19]
	v_cmp_eq_u32_e64 s[18:19], 0, v53
	v_cmp_gt_f32_e64 s[20:21], v58, v55
	s_and_b64 s[18:19], s[18:19], s[20:21]
	v_cndmask_b32_e64 v55, v55, v58, s[18:19]
	v_cndmask_b32_e64 v70, v56, 7, s[18:19]
	v_add_f32_e32 v56, v10, v54
	v_cndmask_b32_e64 v57, v57, v50, s[18:19]
	v_cmp_gt_f32_e64 s[18:19], v56, v55
	s_nop 1
	v_cndmask_b32_e64 v106, v70, 8, s[18:19]
	v_cndmask_b32_e64 v54, v57, 0, s[18:19]
	v_lshl_add_u32 v57, v106, 2, v117
	v_lshl_add_u32 v70, v54, 2, v117
	ds_read_b32 v57, v57 offset:17408
	ds_read_b32 v70, v70 offset:26112
	v_cmp_ne_u32_e64 s[20:21], 15, v54
	s_waitcnt lgkmcnt(0)
	v_lshl_add_u32 v57, v57, 7, v70
	v_mov_b32_e32 v224, v57
	s_and_saveexec_b64 s[22:23], s[20:21]
	s_xor_b64 s[20:21], exec, s[22:23]
	s_cbranch_execz .LBB0_237
	v_lshlrev_b32_e32 v25, 2, v106
	v_lshlrev_b64 v[26:27], v25, 1
	v_lshl_add_u64 v[22:23], v[26:27], 0, v[22:23]
	v_and_b32_e32 v25, 15, v22
	v_bfe_u32 v26, v22, 4, 4
	v_bfe_u32 v27, v22, 8, 4
	v_bfe_u32 v30, v22, 12, 4
	v_bfe_u32 v37, v22, 16, 4
	v_bfe_u32 v41, v22, 20, 4
	v_bfe_u32 v46, v22, 24, 4
	v_lshrrev_b32_e32 v50, 28, v22
	v_lshl_add_u32 v54, v25, 2, v117
	v_lshl_add_u32 v57, v26, 2, v117
	v_lshl_add_u32 v58, v27, 2, v117
	v_lshl_add_u32 v59, v30, 2, v117
	v_lshl_add_u32 v60, v37, 2, v117
	v_lshl_add_u32 v61, v41, 2, v117
	v_lshl_add_u32 v62, v46, 2, v117
	v_lshl_add_u32 v63, v50, 2, v117
	ds_read_b32 v54, v54 offset:8704
	ds_read_b32 v57, v57 offset:8704
	ds_read_b32 v58, v58 offset:8704
	ds_read_b32 v70, v59 offset:8704
	ds_read_b32 v71, v60 offset:8704
	ds_read_b32 v72, v61 offset:8704
	ds_read_b32 v73, v62 offset:8704
	ds_read_b32 v106, v63 offset:8704
	s_waitcnt lgkmcnt(7)
	v_add_f32_e32 v59, v16, v54
	s_waitcnt lgkmcnt(6)
	v_add_f32_e32 v60, v17, v57
	s_waitcnt lgkmcnt(5)
	v_add_f32_e32 v61, v14, v58
	s_waitcnt lgkmcnt(4)
	v_add_f32_e32 v62, v15, v70
	s_waitcnt lgkmcnt(3)
	v_add_f32_e32 v63, v12, v71
	s_waitcnt lgkmcnt(2)
	v_add_f32_e32 v104, v13, v72
	s_waitcnt lgkmcnt(1)
	v_add_f32_e32 v105, v20, v73
	s_waitcnt lgkmcnt(0)
	v_add_f32_e32 v58, v21, v106
	v_mov_b32_e32 v54, v23

; template <int MASK>
; __global__ void __launch_bounds__(256, 2) fwd_megakernel_t(Params p) {
;     ...
;           for (int k = 0; k < 16; k++) {
;             float bv = -3e38f;
;             int bi = 0, bj = 0;
; #pragma unroll
;             for (int i = 0; i <= k; i++) {
;               const int j = (int)((P >> (4 * i)) & 15ull);
;               const float cnd = sv0[i] + l1v[j];
;               if (!((E >> i) & 1u) && cnd > bv) { bv = cnd; bi = i; bj = j; }
;             }
;             best[k] = bv;
;             pidx[ob + k] = li[row * 17 + bi] * 128 + li[(128 + row) * 17 + bj];
;             if (bj == 15) E |= 1u << bi; else P += 1ull << (4 * bi);
.LBB0_239:
	s_or_b64 exec, exec, s[20:21]
	v_cmp_eq_u32_e64 s[20:21], 0, v33
	v_cmp_lt_f32_e64 s[22:23], s43, v59
	s_and_b64 s[20:21], s[20:21], s[22:23]
	v_cndmask_b32_e64 v59, v178, v59, s[20:21]
	v_cndmask_b32_e64 v70, 0, v25, s[20:21]
	v_cmp_eq_u32_e64 s[20:21], 0, v34
	v_cmp_gt_f32_e64 s[22:23], v60, v59
	s_and_b64 s[20:21], s[20:21], s[22:23]
	v_cndmask_b32_e64 v59, v59, v60, s[20:21]
	v_cndmask_b32_e64 v60, 0, 1, s[20:21]
	v_cndmask_b32_e64 v70, v70, v26, s[20:21]
	v_cmp_eq_u32_e64 s[20:21], 0, v36
	v_cmp_gt_f32_e64 s[22:23], v61, v59
	s_and_b64 s[20:21], s[20:21], s[22:23]
	v_cndmask_b32_e64 v59, v59, v61, s[20:21]
	v_cndmask_b32_e64 v60, v60, 2, s[20:21]
	v_cndmask_b32_e64 v61, v70, v27, s[20:21]
	v_cmp_eq_u32_e64 s[20:21], 0, v35
	v_cmp_gt_f32_e64 s[22:23], v62, v59
	s_and_b64 s[20:21], s[20:21], s[22:23]
	v_cndmask_b32_e64 v59, v59, v62, s[20:21]
	v_cndmask_b32_e64 v60, v60, 3, s[20:21]
	v_cndmask_b32_e64 v61, v61, v30, s[20:21]
	v_cmp_eq_u32_e64 s[20:21], 0, v40
	v_cmp_gt_f32_e64 s[22:23], v63, v59
	s_and_b64 s[20:21], s[20:21], s[22:23]
	v_cndmask_b32_e64 v59, v59, v63, s[20:21]
	v_cndmask_b32_e64 v60, v60, 4, s[20:21]
	v_cndmask_b32_e64 v61, v61, v37, s[20:21]
	v_cmp_eq_u32_e64 s[20:21], 0, v44
	v_cmp_gt_f32_e64 s[22:23], v104, v59
	s_and_b64 s[20:21], s[20:21], s[22:23]
	v_cndmask_b32_e64 v59, v59, v104, s[20:21]
	v_lshl_add_u32 v62, v54, 2, v117
	v_cndmask_b32_e64 v60, v60, 5, s[20:21]
	v_cndmask_b32_e64 v61, v61, v41, s[20:21]
	v_cmp_eq_u32_e64 s[20:21], 0, v49
	v_cmp_gt_f32_e64 s[22:23], v105, v59
	ds_read_b32 v62, v62 offset:8704
	s_and_b64 s[20:21], s[20:21], s[22:23]
	v_cndmask_b32_e64 v59, v59, v105, s[20:21]
	v_cndmask_b32_e64 v60, v60, 6, s[20:21]
	v_cndmask_b32_e64 v61, v61, v46, s[20:21]
	v_cmp_eq_u32_e64 s[20:21], 0, v53
	v_cmp_gt_f32_e64 s[22:23], v58, v59
	ds_read_b32 v63, v117 offset:8704
	s_and_b64 s[20:21], s[20:21], s[22:23]
	v_cndmask_b32_e64 v58, v59, v58, s[20:21]
	v_cndmask_b32_e64 v59, v60, 7, s[20:21]
	s_waitcnt lgkmcnt(1)
	v_add_f32_e32 v60, v10, v62
	v_cndmask_b32_e64 v61, v61, v50, s[20:21]
	v_cmp_eq_u32_e64 s[20:21], 0, v57
	v_cmp_gt_f32_e64 s[22:23], v60, v58
	s_and_b64 s[20:21], s[20:21], s[22:23]
	v_cndmask_b32_e64 v60, v58, v60, s[20:21]
	v_cndmask_b32_e64 v58, v59, 8, s[20:21]
	v_cndmask_b32_e64 v59, v61, v54, s[20:21]
	s_waitcnt lgkmcnt(0)
	v_add_f32_e32 v61, v11, v63
	v_cmp_gt_f32_e64 s[20:21], v61, v60
	s_nop 1
	v_cndmask_b32_e64 v62, v58, 9, s[20:21]
	v_cndmask_b32_e64 v58, v59, 0, s[20:21]
	v_lshl_add_u32 v59, v62, 2, v117
	v_lshl_add_u32 v63, v58, 2, v117
	ds_read_b32 v59, v59 offset:17408
	ds_read_b32 v63, v63 offset:26112
	v_cmp_ne_u32_e64 s[22:23], 15, v58
	s_waitcnt lgkmcnt(0)
	v_lshl_add_u32 v59, v59, 7, v63
	v_mov_b32_e32 v225, v59
	s_and_saveexec_b64 s[24:25], s[22:23]
	s_xor_b64 s[22:23], exec, s[24:25]
	s_cbranch_execz .LBB0_241
	v_lshlrev_b32_e32 v25, 2, v62
	v_lshlrev_b64 v[26:27], v25, 1
	v_lshl_add_u64 v[22:23], v[26:27], 0, v[22:23]
	v_and_b32_e32 v25, 15, v22
	v_bfe_u32 v26, v22, 4, 4
	v_bfe_u32 v27, v22, 8, 4
	v_bfe_u32 v30, v22, 12, 4
	v_bfe_u32 v37, v22, 16, 4
	v_bfe_u32 v41, v22, 20, 4
	v_bfe_u32 v46, v22, 24, 4
	v_lshrrev_b32_e32 v50, 28, v22
	v_and_b32_e32 v54, 15, v23
	v_lshrrev_b32_e32 v58, 4, v23

; template <int MASK>
; __global__ void __launch_bounds__(256, 2) fwd_megakernel_t(Params p) {
;     ...
;           for (int k = 0; k < 16; k++) {
;             float bv = -3e38f;
;             int bi = 0, bj = 0;
; #pragma unroll
;             for (int i = 0; i <= k; i++) {
;               const int j = (int)((P >> (4 * i)) & 15ull);
;               const float cnd = sv0[i] + l1v[j];
;               if (!((E >> i) & 1u) && cnd > bv) { bv = cnd; bi = i; bj = j; }
;             }
;             best[k] = bv;
;             pidx[ob + k] = li[row * 17 + bi] * 128 + li[(128 + row) * 17 + bj];
;             if (bj == 15) E |= 1u << bi; else P += 1ull << (4 * bi);
.LBB0_243:
	s_or_b64 exec, exec, s[22:23]
	v_lshl_add_u32 v62, v25, 2, v117
	v_lshl_add_u32 v63, v26, 2, v117
	v_lshl_add_u32 v70, v27, 2, v117
	v_lshl_add_u32 v71, v30, 2, v117
	v_lshl_add_u32 v72, v37, 2, v117
	v_lshl_add_u32 v73, v41, 2, v117
	v_lshl_add_u32 v104, v46, 2, v117
	ds_read_b32 v62, v62 offset:8704
	ds_read_b32 v63, v63 offset:8704
	ds_read_b32 v70, v70 offset:8704
	ds_read_b32 v71, v71 offset:8704
	ds_read_b32 v72, v72 offset:8704
	ds_read_b32 v73, v73 offset:8704
	ds_read_b32 v104, v104 offset:8704
	ds_read_b32 v105, v117 offset:8704
	s_waitcnt lgkmcnt(7)
	v_add_f32_e32 v62, v16, v62
	v_cmp_eq_u32_e64 s[22:23], 0, v33
	v_cmp_lt_f32_e64 s[24:25], s43, v62
	s_and_b64 s[22:23], s[22:23], s[24:25]
	v_cndmask_b32_e64 v62, v178, v62, s[22:23]
	s_waitcnt lgkmcnt(6)
	v_add_f32_e32 v63, v17, v63
	v_cndmask_b32_e64 v106, 0, v25, s[22:23]
	v_cmp_eq_u32_e64 s[22:23], 0, v34
	v_cmp_gt_f32_e64 s[24:25], v63, v62
	s_and_b64 s[22:23], s[22:23], s[24:25]
	v_cndmask_b32_e64 v62, v62, v63, s[22:23]
	v_cndmask_b32_e64 v107, v106, v26, s[22:23]
	s_waitcnt lgkmcnt(5)
	v_add_f32_e32 v106, v14, v70
	v_cndmask_b32_e64 v63, 0, 1, s[22:23]
	v_cmp_eq_u32_e64 s[22:23], 0, v36
	v_cmp_gt_f32_e64 s[24:25], v106, v62
	s_and_b64 s[22:23], s[22:23], s[24:25]
	v_cndmask_b32_e64 v62, v62, v106, s[22:23]
	v_cndmask_b32_e64 v70, v107, v27, s[22:23]
	s_waitcnt lgkmcnt(4)
	v_add_f32_e32 v107, v15, v71
	v_cndmask_b32_e64 v63, v63, 2, s[22:23]
	v_cmp_eq_u32_e64 s[22:23], 0, v35
	v_cmp_gt_f32_e64 s[24:25], v107, v62
	s_and_b64 s[22:23], s[22:23], s[24:25]
	v_cndmask_b32_e64 v62, v62, v107, s[22:23]
	s_waitcnt lgkmcnt(3)
	v_add_f32_e32 v108, v12, v72
	v_cndmask_b32_e64 v63, v63, 3, s[22:23]
	v_cndmask_b32_e64 v70, v70, v30, s[22:23]
	v_cmp_eq_u32_e64 s[22:23], 0, v40
	v_cmp_gt_f32_e64 s[24:25], v108, v62
	s_and_b64 s[22:23], s[22:23], s[24:25]
	v_cndmask_b32_e64 v62, v62, v108, s[22:23]
	s_waitcnt lgkmcnt(2)
	v_add_f32_e32 v109, v13, v73
	v_lshl_add_u32 v71, v50, 2, v117
	v_cndmask_b32_e64 v63, v63, 4, s[22:23]
	v_cndmask_b32_e64 v70, v70, v37, s[22:23]
	v_cmp_eq_u32_e64 s[22:23], 0, v44
	v_cmp_gt_f32_e64 s[24:25], v109, v62
	ds_read_b32 v71, v71 offset:8704
	s_and_b64 s[22:23], s[22:23], s[24:25]
	v_cndmask_b32_e64 v62, v62, v109, s[22:23]
	s_waitcnt lgkmcnt(2)
	v_add_f32_e32 v118, v20, v104
	v_cndmask_b32_e64 v63, v63, 5, s[22:23]
	v_cndmask_b32_e64 v70, v70, v41, s[22:23]
	v_cmp_eq_u32_e64 s[22:23], 0, v49
	v_cmp_gt_f32_e64 s[24:25], v118, v62
	v_lshl_add_u32 v72, v54, 2, v117
	v_lshl_add_u32 v73, v58, 2, v117
	s_and_b64 s[22:23], s[22:23], s[24:25]
	ds_read_b32 v72, v72 offset:8704
	ds_read_b32 v73, v73 offset:8704
	v_cndmask_b32_e64 v62, v62, v118, s[22:23]
	s_waitcnt lgkmcnt(2)
	v_add_f32_e32 v119, v21, v71
	v_cndmask_b32_e64 v63, v63, 6, s[22:23]
	v_cndmask_b32_e64 v70, v70, v46, s[22:23]
	v_cmp_eq_u32_e64 s[22:23], 0, v53
	v_cmp_gt_f32_e64 s[24:25], v119, v62
	s_and_b64 s[22:23], s[22:23], s[24:25]
	v_cndmask_b32_e64 v62, v62, v119, s[22:23]
	s_waitcnt lgkmcnt(1)
	v_add_f32_e32 v120, v10, v72
	v_cndmask_b32_e64 v63, v63, 7, s[22:23]
	v_cndmask_b32_e64 v70, v70, v50, s[22:23]
	v_cmp_eq_u32_e64 s[22:23], 0, v57
	v_cmp_gt_f32_e64 s[24:25], v120, v62
	s_and_b64 s[22:23], s[22:23], s[24:25]
	v_cndmask_b32_e64 v62, v62, v120, s[22:23]
	s_waitcnt lgkmcnt(0)
	v_add_f32_e32 v121, v11, v73
	v_cndmask_b32_e64 v71, v63, 8, s[22:23]
	v_cndmask_b32_e64 v70, v70, v54, s[22:23]
	v_cmp_eq_u32_e64 s[22:23], 0, v59
	v_cmp_gt_f32_e64 s[24:25], v121, v62
	s_and_b64 s[22:23], s[22:23], s[24:25]
	v_cndmask_b32_e64 v63, v62, v121, s[22:23]
	v_add_f32_e32 v104, v8, v105
	v_cndmask_b32_e64 v62, v71, 9, s[22:23]
	v_cndmask_b32_e64 v70, v70, v58, s[22:23]
	v_cmp_gt_f32_e64 s[22:23], v104, v63
	s_nop 1
	v_cndmask_b32_e64 v110, v62, 10, s[22:23]
	v_cndmask_b32_e64 v62, v70, 0, s[22:23]
	v_lshl_add_u32 v70, v110, 2, v117
	v_lshl_add_u32 v71, v62, 2, v117
	ds_read_b32 v70, v70 offset:17408
	ds_read_b32 v71, v71 offset:26112
	v_cmp_ne_u32_e64 s[24:25], 15, v62
	s_waitcnt lgkmcnt(0)
	v_lshl_add_u32 v70, v70, 7, v71
	v_mov_b32_e32 v226, v70
	s_and_saveexec_b64 s[26:27], s[24:25]
	s_xor_b64 s[24:25], exec, s[26:27]
	s_cbranch_execz .LBB0_245
	v_lshlrev_b32_e32 v25, 2, v110
	v_lshlrev_b64 v[26:27], v25, 1
	v_lshl_add_u64 v[22:23], v[26:27], 0, v[22:23]
	v_bfe_u32 v27, v22, 8, 4
	v_bfe_u32 v30, v22, 12, 4
	v_bfe_u32 v37, v22, 16, 4
	v_bfe_u32 v41, v22, 20, 4
	v_bfe_u32 v46, v22, 24, 4
	v_lshrrev_b32_e32 v50, 28, v22
	v_and_b32_e32 v54, 15, v23
	v_bfe_u32 v58, v23, 4, 4
	v_lshl_add_u32 v70, v27, 2, v117
	v_lshl_add_u32 v71, v30, 2, v117
	v_lshl_add_u32 v72, v37, 2, v117
	v_lshl_add_u32 v73, v41, 2, v117
	v_lshl_add_u32 v105, v46, 2, v117
	v_lshl_add_u32 v106, v50, 2, v117
	v_lshl_add_u32 v107, v54, 2, v117
	v_lshl_add_u32 v108, v58, 2, v117
	ds_read_b32 v70, v70 offset:8704
	ds_read_b32 v71, v71 offset:8704
	ds_read_b32 v72, v72 offset:8704
	ds_read_b32 v73, v73 offset:8704
	ds_read_b32 v105, v105 offset:8704
	ds_read_b32 v110, v106 offset:8704
	ds_read_b32 v111, v107 offset:8704
	ds_read_b32 v121, v108 offset:8704
	v_and_b32_e32 v25, 15, v22
	v_bfe_u32 v26, v22, 4, 4
	v_lshrrev_b32_e32 v62, 8, v23
	s_waitcnt lgkmcnt(7)
	v_add_f32_e32 v106, v14, v70
	s_waitcnt lgkmcnt(6)
	v_add_f32_e32 v107, v15, v71
	s_waitcnt lgkmcnt(5)
	v_add_f32_e32 v108, v12, v72
	s_waitcnt lgkmcnt(4)
	v_add_f32_e32 v109, v13, v73
	s_waitcnt lgkmcnt(3)
	v_add_f32_e32 v118, v20, v105
	s_waitcnt lgkmcnt(2)
	v_add_f32_e32 v119, v21, v110
	s_waitcnt lgkmcnt(1)
	v_add_f32_e32 v120, v10, v111
	s_waitcnt lgkmcnt(0)
	v_add_f32_e32 v121, v11, v121

; template <int MASK>
; __global__ void __launch_bounds__(256, 2) fwd_megakernel_t(Params p) {
;     ...
;           for (int k = 0; k < 16; k++) {
;             float bv = -3e38f;
;             int bi = 0, bj = 0;
; #pragma unroll
;             for (int i = 0; i <= k; i++) {
;               const int j = (int)((P >> (4 * i)) & 15ull);
;               const float cnd = sv0[i] + l1v[j];
;               if (!((E >> i) & 1u) && cnd > bv) { bv = cnd; bi = i; bj = j; }
;             }
;             best[k] = bv;
;             pidx[ob + k] = li[row * 17 + bi] * 128 + li[(128 + row) * 17 + bj];
;             if (bj == 15) E |= 1u << bi; else P += 1ull << (4 * bi);
.LBB0_247:
	s_or_b64 exec, exec, s[24:25]
	v_lshl_add_u32 v70, v25, 2, v117
	ds_read_b32 v70, v70 offset:8704
	v_lshl_add_u32 v72, v26, 2, v117
	ds_read_b32 v72, v72 offset:8704
	v_cmp_eq_u32_e64 s[24:25], 0, v33
	v_lshl_add_u32 v73, v62, 2, v117
	s_waitcnt lgkmcnt(1)
	v_add_f32_e32 v110, v16, v70
	v_cmp_lt_f32_e64 s[26:27], s43, v110
	s_and_b64 s[24:25], s[24:25], s[26:27]
	v_cndmask_b32_e64 v70, v178, v110, s[24:25]
	s_waitcnt lgkmcnt(0)
	v_add_f32_e32 v111, v17, v72
	v_cndmask_b32_e64 v71, 0, v25, s[24:25]
	v_cmp_eq_u32_e64 s[24:25], 0, v34
	v_cmp_gt_f32_e64 s[26:27], v111, v70
	s_and_b64 s[24:25], s[24:25], s[26:27]
	v_cndmask_b32_e64 v70, v70, v111, s[24:25]
	v_cndmask_b32_e64 v72, 0, 1, s[24:25]
	v_cndmask_b32_e64 v71, v71, v26, s[24:25]
	v_cmp_eq_u32_e64 s[24:25], 0, v36
	v_cmp_gt_f32_e64 s[26:27], v106, v70
	s_and_b64 s[24:25], s[24:25], s[26:27]
	v_cndmask_b32_e64 v70, v70, v106, s[24:25]
	v_cndmask_b32_e64 v72, v72, 2, s[24:25]
	v_cndmask_b32_e64 v71, v71, v27, s[24:25]
	v_cmp_eq_u32_e64 s[24:25], 0, v35
	v_cmp_gt_f32_e64 s[26:27], v107, v70
	s_and_b64 s[24:25], s[24:25], s[26:27]
	v_cndmask_b32_e64 v70, v70, v107, s[24:25]
	v_cndmask_b32_e64 v72, v72, 3, s[24:25]
	v_cndmask_b32_e64 v71, v71, v30, s[24:25]
	v_cmp_eq_u32_e64 s[24:25], 0, v40
	v_cmp_gt_f32_e64 s[26:27], v108, v70
	s_and_b64 s[24:25], s[24:25], s[26:27]
	v_cndmask_b32_e64 v70, v70, v108, s[24:25]
	v_cndmask_b32_e64 v72, v72, 4, s[24:25]
	v_cndmask_b32_e64 v71, v71, v37, s[24:25]
	v_cmp_eq_u32_e64 s[24:25], 0, v44
	v_cmp_gt_f32_e64 s[26:27], v109, v70
	s_and_b64 s[24:25], s[24:25], s[26:27]
	v_cndmask_b32_e64 v70, v70, v109, s[24:25]
	v_cndmask_b32_e64 v72, v72, 5, s[24:25]
	v_cndmask_b32_e64 v71, v71, v41, s[24:25]
	v_cmp_eq_u32_e64 s[24:25], 0, v49
	v_cmp_gt_f32_e64 s[26:27], v118, v70
	s_and_b64 s[24:25], s[24:25], s[26:27]
	v_cndmask_b32_e64 v70, v70, v118, s[24:25]
	v_cndmask_b32_e64 v72, v72, 6, s[24:25]
	v_cndmask_b32_e64 v71, v71, v46, s[24:25]
	v_cmp_eq_u32_e64 s[24:25], 0, v53
	v_cmp_gt_f32_e64 s[26:27], v119, v70
	s_and_b64 s[24:25], s[24:25], s[26:27]
	v_cndmask_b32_e64 v70, v70, v119, s[24:25]
	v_cndmask_b32_e64 v72, v72, 7, s[24:25]
	v_cndmask_b32_e64 v71, v71, v50, s[24:25]
	v_cmp_eq_u32_e64 s[24:25], 0, v57
	v_cmp_gt_f32_e64 s[26:27], v120, v70
	ds_read_b32 v73, v73 offset:8704
	s_and_b64 s[24:25], s[24:25], s[26:27]
	v_cndmask_b32_e64 v70, v70, v120, s[24:25]
	v_cndmask_b32_e64 v72, v72, 8, s[24:25]
	v_cndmask_b32_e64 v71, v71, v54, s[24:25]
	v_cmp_eq_u32_e64 s[24:25], 0, v59
	v_cmp_gt_f32_e64 s[26:27], v121, v70
	s_and_b64 s[24:25], s[24:25], s[26:27]
	v_cndmask_b32_e64 v70, v70, v121, s[24:25]
	s_waitcnt lgkmcnt(0)
	v_add_f32_e32 v73, v8, v73
	v_cndmask_b32_e64 v72, v72, 9, s[24:25]
	v_cndmask_b32_e64 v71, v71, v58, s[24:25]
	v_cmp_eq_u32_e64 s[24:25], 0, v105
	v_cmp_gt_f32_e64 s[26:27], v73, v70
	s_and_b64 s[24:25], s[24:25], s[26:27]
	v_cndmask_b32_e64 v106, v70, v73, s[24:25]
	v_cndmask_b32_e64 v70, v72, 10, s[24:25]
	ds_read_b32 v72, v117 offset:8704
	v_cndmask_b32_e64 v71, v71, v62, s[24:25]
	s_waitcnt lgkmcnt(0)
	v_add_f32_e32 v108, v9, v72
	v_cmp_gt_f32_e64 s[24:25], v108, v106
	s_nop 1
	v_cndmask_b32_e64 v118, v70, 11, s[24:25]
	v_cndmask_b32_e64 v70, v71, 0, s[24:25]
	v_lshl_add_u32 v71, v118, 2, v117
	v_lshl_add_u32 v72, v70, 2, v117
	ds_read_b32 v71, v71 offset:17408
	ds_read_b32 v72, v72 offset:26112
	v_cmp_ne_u32_e64 s[26:27], 15, v70
	s_waitcnt lgkmcnt(0)
	v_lshl_add_u32 v71, v71, 7, v72
	v_mov_b32_e32 v227, v71
	s_and_saveexec_b64 s[28:29], s[26:27]
	s_xor_b64 s[26:27], exec, s[28:29]
	s_cbranch_execz .LBB0_249
	v_lshlrev_b32_e32 v25, 2, v118
	v_lshlrev_b64 v[26:27], v25, 1
	v_lshl_add_u64 v[22:23], v[26:27], 0, v[22:23]
	v_and_b32_e32 v25, 15, v22
	v_bfe_u32 v26, v22, 4, 4
	v_lshl_add_u32 v58, v25, 2, v117
	v_lshl_add_u32 v62, v26, 2, v117
	ds_read_b32 v70, v58 offset:8704
	ds_read_b32 v71, v62 offset:8704
	v_bfe_u32 v27, v22, 8, 4
	v_bfe_u32 v30, v22, 12, 4
	v_bfe_u32 v37, v22, 16, 4
	v_bfe_u32 v41, v22, 20, 4
	v_bfe_u32 v46, v22, 24, 4
	v_lshrrev_b32_e32 v50, 28, v22
	v_and_b32_e32 v54, 15, v23
	v_bfe_u32 v58, v23, 4, 4
	v_bfe_u32 v62, v23, 8, 4
	v_lshrrev_b32_e32 v107, 12, v23
	s_waitcnt lgkmcnt(1)
	v_add_f32_e32 v110, v16, v70
	s_waitcnt lgkmcnt(0)
	v_add_f32_e32 v111, v17, v71

; template <int MASK>
; __global__ void __launch_bounds__(256, 2) fwd_megakernel_t(Params p) {
;     ...
;           for (int k = 0; k < 16; k++) {
;             float bv = -3e38f;
;             int bi = 0, bj = 0;
; #pragma unroll
;             for (int i = 0; i <= k; i++) {
;               const int j = (int)((P >> (4 * i)) & 15ull);
;               const float cnd = sv0[i] + l1v[j];
;               if (!((E >> i) & 1u) && cnd > bv) { bv = cnd; bi = i; bj = j; }
;             }
;             best[k] = bv;
;             pidx[ob + k] = li[row * 17 + bi] * 128 + li[(128 + row) * 17 + bj];
;             if (bj == 15) E |= 1u << bi; else P += 1ull << (4 * bi);
.LBB0_251:
	s_or_b64 exec, exec, s[26:27]
	v_lshl_add_u32 v73, v27, 2, v117
	v_cmp_eq_u32_e64 s[26:27], 0, v33
	v_cmp_lt_f32_e64 s[28:29], s43, v110
	ds_read_b32 v73, v73 offset:8704
	s_and_b64 s[26:27], s[26:27], s[28:29]
	v_cndmask_b32_e64 v70, v178, v110, s[26:27]
	v_cndmask_b32_e64 v71, 0, v25, s[26:27]
	v_cmp_eq_u32_e64 s[26:27], 0, v34
	v_cmp_gt_f32_e64 s[28:29], v111, v70
	s_and_b64 s[26:27], s[26:27], s[28:29]
	v_cndmask_b32_e64 v70, v70, v111, s[26:27]
	s_waitcnt lgkmcnt(0)
	v_add_f32_e32 v73, v14, v73
	v_cndmask_b32_e64 v72, 0, 1, s[26:27]
	v_cndmask_b32_e64 v71, v71, v26, s[26:27]
	v_cmp_eq_u32_e64 s[26:27], 0, v36
	v_cmp_gt_f32_e64 s[28:29], v73, v70
	s_and_b64 s[26:27], s[26:27], s[28:29]
	v_cndmask_b32_e64 v70, v70, v73, s[26:27]
	v_lshl_add_u32 v73, v30, 2, v117
	ds_read_b32 v73, v73 offset:8704
	v_cndmask_b32_e64 v72, v72, 2, s[26:27]
	v_cndmask_b32_e64 v71, v71, v27, s[26:27]
	v_cmp_eq_u32_e64 s[26:27], 0, v35
	s_waitcnt lgkmcnt(0)
	v_add_f32_e32 v73, v15, v73
	v_cmp_gt_f32_e64 s[28:29], v73, v70
	s_and_b64 s[26:27], s[26:27], s[28:29]
	v_cndmask_b32_e64 v70, v70, v73, s[26:27]
	v_lshl_add_u32 v73, v37, 2, v117
	ds_read_b32 v73, v73 offset:8704
	v_cndmask_b32_e64 v72, v72, 3, s[26:27]
	v_cndmask_b32_e64 v71, v71, v30, s[26:27]
	v_cmp_eq_u32_e64 s[26:27], 0, v40
	s_waitcnt lgkmcnt(0)
	v_add_f32_e32 v120, v12, v73
	v_lshl_add_u32 v73, v41, 2, v117
	ds_read_b32 v73, v73 offset:8704
	v_cmp_gt_f32_e64 s[28:29], v120, v70
	s_and_b64 s[26:27], s[26:27], s[28:29]
	v_cndmask_b32_e64 v70, v70, v120, s[26:27]
	v_cndmask_b32_e64 v72, v72, 4, s[26:27]
	s_waitcnt lgkmcnt(0)
	v_add_f32_e32 v121, v13, v73
	v_lshl_add_u32 v73, v46, 2, v117
	ds_read_b32 v73, v73 offset:8704
	v_cndmask_b32_e64 v71, v71, v37, s[26:27]
	v_cmp_eq_u32_e64 s[26:27], 0, v44
	v_cmp_gt_f32_e64 s[28:29], v121, v70
	s_and_b64 s[26:27], s[26:27], s[28:29]
	s_waitcnt lgkmcnt(0)
	v_add_f32_e32 v122, v20, v73
	v_lshl_add_u32 v73, v50, 2, v117
	ds_read_b32 v73, v73 offset:8704
	v_cndmask_b32_e64 v70, v70, v121, s[26:27]
	v_cndmask_b32_e64 v72, v72, 5, s[26:27]
	v_cndmask_b32_e64 v71, v71, v41, s[26:27]
	v_cmp_eq_u32_e64 s[26:27], 0, v49
	s_waitcnt lgkmcnt(0)
	v_add_f32_e32 v123, v21, v73
	v_lshl_add_u32 v73, v54, 2, v117
	ds_read_b32 v73, v73 offset:8704
	v_cmp_gt_f32_e64 s[28:29], v122, v70
	s_and_b64 s[26:27], s[26:27], s[28:29]
	v_cndmask_b32_e64 v70, v70, v122, s[26:27]
	v_cndmask_b32_e64 v72, v72, 6, s[26:27]
	s_waitcnt lgkmcnt(0)
	v_add_f32_e32 v125, v10, v73
	v_lshl_add_u32 v73, v58, 2, v117
	v_cndmask_b32_e64 v71, v71, v46, s[26:27]
	v_cmp_eq_u32_e64 s[26:27], 0, v53
	v_cmp_gt_f32_e64 s[28:29], v123, v70
	ds_read_b32 v73, v73 offset:8704
	s_and_b64 s[26:27], s[26:27], s[28:29]
	v_cndmask_b32_e64 v70, v70, v123, s[26:27]
	v_cndmask_b32_e64 v72, v72, 7, s[26:27]
	v_cndmask_b32_e64 v71, v71, v50, s[26:27]
	v_cmp_eq_u32_e64 s[26:27], 0, v57
	v_cmp_gt_f32_e64 s[28:29], v125, v70
	s_and_b64 s[26:27], s[26:27], s[28:29]
	v_cndmask_b32_e64 v70, v70, v125, s[26:27]
	s_waitcnt lgkmcnt(0)
	v_add_f32_e32 v73, v11, v73
	v_cndmask_b32_e64 v72, v72, 8, s[26:27]
	v_cndmask_b32_e64 v71, v71, v54, s[26:27]
	v_cmp_eq_u32_e64 s[26:27], 0, v59
	v_cmp_gt_f32_e64 s[28:29], v73, v70
	s_and_b64 s[26:27], s[26:27], s[28:29]
	v_cndmask_b32_e64 v70, v70, v73, s[26:27]
	v_lshl_add_u32 v73, v62, 2, v117
	ds_read_b32 v73, v73 offset:8704
	v_cndmask_b32_e64 v72, v72, 9, s[26:27]
	v_cndmask_b32_e64 v71, v71, v58, s[26:27]
	v_cmp_eq_u32_e64 s[26:27], 0, v105
	s_waitcnt lgkmcnt(0)
	v_add_f32_e32 v73, v8, v73
	v_cmp_gt_f32_e64 s[28:29], v73, v70
	s_and_b64 s[26:27], s[26:27], s[28:29]
	v_cndmask_b32_e64 v70, v70, v73, s[26:27]
	v_lshl_add_u32 v73, v107, 2, v117
	ds_read_b32 v73, v73 offset:8704
	v_cndmask_b32_e64 v72, v72, 10, s[26:27]
	v_cndmask_b32_e64 v71, v71, v62, s[26:27]
	v_cmp_eq_u32_e64 s[26:27], 0, v109
	s_waitcnt lgkmcnt(0)
	v_add_f32_e32 v73, v9, v73
	v_cmp_gt_f32_e64 s[28:29], v73, v70
	s_and_b64 s[26:27], s[26:27], s[28:29]
	v_cndmask_b32_e64 v110, v70, v73, s[26:27]
	v_cndmask_b32_e64 v70, v72, 11, s[26:27]
	ds_read_b32 v72, v117 offset:8704
	v_cndmask_b32_e64 v71, v71, v107, s[26:27]
	s_waitcnt lgkmcnt(0)
	v_add_f32_e32 v118, v6, v72
	v_cmp_gt_f32_e64 s[26:27], v118, v110
	s_nop 1
	v_cndmask_b32_e64 v124, v70, 12, s[26:27]
	v_cndmask_b32_e64 v70, v71, 0, s[26:27]
	v_lshl_add_u32 v71, v124, 2, v117
	v_lshl_add_u32 v72, v70, 2, v117
	ds_read_b32 v71, v71 offset:17408
	ds_read_b32 v72, v72 offset:26112
	v_cmp_ne_u32_e64 s[28:29], 15, v70
	s_waitcnt lgkmcnt(0)
	v_lshl_add_u32 v71, v71, 7, v72
	v_mov_b32_e32 v228, v71
	s_and_saveexec_b64 s[30:31], s[28:29]
	s_xor_b64 s[28:29], exec, s[30:31]
	s_cbranch_execz .LBB0_253
	v_lshlrev_b32_e32 v25, 2, v124
	v_lshlrev_b64 v[26:27], v25, 1
	v_lshl_add_u64 v[22:23], v[26:27], 0, v[22:23]
	v_bfe_u32 v37, v22, 16, 4
	v_bfe_u32 v41, v22, 20, 4
	v_bfe_u32 v46, v22, 24, 4
	v_lshrrev_b32_e32 v50, 28, v22
	v_and_b32_e32 v54, 15, v23
	v_lshl_add_u32 v70, v37, 2, v117
	v_lshl_add_u32 v71, v41, 2, v117
	v_lshl_add_u32 v72, v46, 2, v117
	v_lshl_add_u32 v73, v50, 2, v117
	v_lshl_add_u32 v119, v54, 2, v117
	ds_read_b32 v70, v70 offset:8704
	ds_read_b32 v71, v71 offset:8704
	ds_read_b32 v72, v72 offset:8704
	ds_read_b32 v73, v73 offset:8704
	ds_read_b32 v119, v119 offset:8704
	v_and_b32_e32 v25, 15, v22
	v_bfe_u32 v26, v22, 4, 4
	v_bfe_u32 v27, v22, 8, 4
	v_bfe_u32 v30, v22, 12, 4
	v_bfe_u32 v58, v23, 4, 4
	v_bfe_u32 v62, v23, 8, 4
	v_bfe_u32 v107, v23, 12, 4
	v_lshrrev_b32_e32 v111, 16, v23
	s_waitcnt lgkmcnt(4)
	v_add_f32_e32 v120, v12, v70
	s_waitcnt lgkmcnt(3)
	v_add_f32_e32 v121, v13, v71
	s_waitcnt lgkmcnt(2)
	v_add_f32_e32 v122, v20, v72
	s_waitcnt lgkmcnt(1)
	v_add_f32_e32 v123, v21, v73
	s_waitcnt lgkmcnt(0)
	v_add_f32_e32 v125, v10, v119

; template <int MASK>
; __global__ void __launch_bounds__(256, 2) fwd_megakernel_t(Params p) {
;     ...
;           for (int k = 0; k < 16; k++) {
;             float bv = -3e38f;
;             int bi = 0, bj = 0;
; #pragma unroll
;             for (int i = 0; i <= k; i++) {
;               const int j = (int)((P >> (4 * i)) & 15ull);
;               const float cnd = sv0[i] + l1v[j];
;               if (!((E >> i) & 1u) && cnd > bv) { bv = cnd; bi = i; bj = j; }
;             }
;             best[k] = bv;
;             pidx[ob + k] = li[row * 17 + bi] * 128 + li[(128 + row) * 17 + bj];
;             if (bj == 15) E |= 1u << bi; else P += 1ull << (4 * bi);
.LBB0_255:
	s_or_b64 exec, exec, s[28:29]
	v_lshl_add_u32 v70, v25, 2, v117
	ds_read_b32 v70, v70 offset:8704
	v_lshl_add_u32 v72, v26, 2, v117
	ds_read_b32 v72, v72 offset:8704
	v_lshl_add_u32 v73, v27, 2, v117
	v_cmp_eq_u32_e64 s[28:29], 0, v33
	s_waitcnt lgkmcnt(1)
	v_add_f32_e32 v70, v16, v70
	v_cmp_lt_f32_e64 s[30:31], s43, v70
	ds_read_b32 v73, v73 offset:8704
	s_and_b64 s[28:29], s[28:29], s[30:31]
	v_cndmask_b32_e64 v70, v178, v70, s[28:29]
	s_waitcnt lgkmcnt(1)
	v_add_f32_e32 v72, v17, v72
	v_cndmask_b32_e64 v71, 0, v25, s[28:29]
	v_cmp_eq_u32_e64 s[28:29], 0, v34
	v_cmp_gt_f32_e64 s[30:31], v72, v70
	s_and_b64 s[28:29], s[28:29], s[30:31]
	v_cndmask_b32_e64 v70, v70, v72, s[28:29]
	s_waitcnt lgkmcnt(0)
	v_add_f32_e32 v73, v14, v73
	v_cndmask_b32_e64 v72, 0, 1, s[28:29]
	v_cndmask_b32_e64 v71, v71, v26, s[28:29]
	v_cmp_eq_u32_e64 s[28:29], 0, v36
	v_cmp_gt_f32_e64 s[30:31], v73, v70
	s_and_b64 s[28:29], s[28:29], s[30:31]
	v_cndmask_b32_e64 v70, v70, v73, s[28:29]
	v_lshl_add_u32 v73, v30, 2, v117
	ds_read_b32 v73, v73 offset:8704
	v_cndmask_b32_e64 v72, v72, 2, s[28:29]
	v_cndmask_b32_e64 v71, v71, v27, s[28:29]
	v_cmp_eq_u32_e64 s[28:29], 0, v35
	s_waitcnt lgkmcnt(0)
	v_add_f32_e32 v124, v15, v73
	v_cmp_gt_f32_e64 s[30:31], v124, v70
	s_and_b64 s[28:29], s[28:29], s[30:31]
	v_cndmask_b32_e64 v70, v70, v124, s[28:29]
	v_cndmask_b32_e64 v72, v72, 3, s[28:29]
	v_cndmask_b32_e64 v71, v71, v30, s[28:29]
	v_cmp_eq_u32_e64 s[28:29], 0, v40
	v_cmp_gt_f32_e64 s[30:31], v120, v70
	s_and_b64 s[28:29], s[28:29], s[30:31]
	v_cndmask_b32_e64 v70, v70, v120, s[28:29]
	v_cndmask_b32_e64 v72, v72, 4, s[28:29]
	v_cndmask_b32_e64 v71, v71, v37, s[28:29]
	v_cmp_eq_u32_e64 s[28:29], 0, v44
	v_cmp_gt_f32_e64 s[30:31], v121, v70
	s_and_b64 s[28:29], s[28:29], s[30:31]
	v_cndmask_b32_e64 v70, v70, v121, s[28:29]
	v_cndmask_b32_e64 v72, v72, 5, s[28:29]
	v_cndmask_b32_e64 v71, v71, v41, s[28:29]
	v_cmp_eq_u32_e64 s[28:29], 0, v49
	v_cmp_gt_f32_e64 s[30:31], v122, v70
	s_and_b64 s[28:29], s[28:29], s[30:31]
	v_cndmask_b32_e64 v70, v70, v122, s[28:29]
	v_lshl_add_u32 v73, v58, 2, v117
	v_cndmask_b32_e64 v72, v72, 6, s[28:29]
	v_cndmask_b32_e64 v71, v71, v46, s[28:29]
	v_cmp_eq_u32_e64 s[28:29], 0, v53
	v_cmp_gt_f32_e64 s[30:31], v123, v70
	ds_read_b32 v73, v73 offset:8704
	s_and_b64 s[28:29], s[28:29], s[30:31]
	v_cndmask_b32_e64 v70, v70, v123, s[28:29]
	v_cndmask_b32_e64 v72, v72, 7, s[28:29]
	v_cndmask_b32_e64 v71, v71, v50, s[28:29]
	v_cmp_eq_u32_e64 s[28:29], 0, v57
	v_cmp_gt_f32_e64 s[30:31], v125, v70
	s_and_b64 s[28:29], s[28:29], s[30:31]
	v_cndmask_b32_e64 v70, v70, v125, s[28:29]
	s_waitcnt lgkmcnt(0)
	v_add_f32_e32 v73, v11, v73
	v_cndmask_b32_e64 v72, v72, 8, s[28:29]
	v_cndmask_b32_e64 v71, v71, v54, s[28:29]
	v_cmp_eq_u32_e64 s[28:29], 0, v59
	v_cmp_gt_f32_e64 s[30:31], v73, v70
	s_and_b64 s[28:29], s[28:29], s[30:31]
	v_cndmask_b32_e64 v70, v70, v73, s[28:29]
	v_lshl_add_u32 v73, v62, 2, v117
	ds_read_b32 v73, v73 offset:8704
	v_cndmask_b32_e64 v72, v72, 9, s[28:29]
	v_cndmask_b32_e64 v71, v71, v58, s[28:29]
	v_cmp_eq_u32_e64 s[28:29], 0, v105
	s_waitcnt lgkmcnt(0)
	v_add_f32_e32 v73, v8, v73
	v_cmp_gt_f32_e64 s[30:31], v73, v70
	s_and_b64 s[28:29], s[28:29], s[30:31]
	v_cndmask_b32_e64 v70, v70, v73, s[28:29]
	v_lshl_add_u32 v73, v107, 2, v117
	ds_read_b32 v73, v73 offset:8704
	v_cndmask_b32_e64 v72, v72, 10, s[28:29]
	v_cndmask_b32_e64 v71, v71, v62, s[28:29]
	v_cmp_eq_u32_e64 s[28:29], 0, v109
	s_waitcnt lgkmcnt(0)
	v_add_f32_e32 v73, v9, v73
	v_cmp_gt_f32_e64 s[30:31], v73, v70
	s_and_b64 s[28:29], s[28:29], s[30:31]
	v_cndmask_b32_e64 v70, v70, v73, s[28:29]
	v_lshl_add_u32 v73, v111, 2, v117
	ds_read_b32 v73, v73 offset:8704
	v_cndmask_b32_e64 v72, v72, 11, s[28:29]
	v_cndmask_b32_e64 v71, v71, v107, s[28:29]
	v_cmp_eq_u32_e64 s[28:29], 0, v119
	s_waitcnt lgkmcnt(0)
	v_add_f32_e32 v73, v6, v73
	v_cmp_gt_f32_e64 s[30:31], v73, v70
	s_and_b64 s[28:29], s[28:29], s[30:31]
	v_cndmask_b32_e64 v120, v70, v73, s[28:29]
	v_cndmask_b32_e64 v70, v72, 12, s[28:29]
	ds_read_b32 v72, v117 offset:8704
	v_cndmask_b32_e64 v71, v71, v111, s[28:29]
	s_waitcnt lgkmcnt(0)
	v_add_f32_e32 v123, v7, v72
	v_cmp_gt_f32_e64 s[28:29], v123, v120
	s_nop 1
	v_cndmask_b32_e64 v125, v70, 13, s[28:29]
	v_cndmask_b32_e64 v70, v71, 0, s[28:29]
	v_lshl_add_u32 v71, v125, 2, v117
	v_lshl_add_u32 v72, v70, 2, v117
	ds_read_b32 v71, v71 offset:17408
	ds_read_b32 v72, v72 offset:26112
	v_cmp_ne_u32_e64 s[30:31], 15, v70
	s_waitcnt lgkmcnt(0)
	v_lshl_add_u32 v71, v71, 7, v72
	v_mov_b32_e32 v229, v71
	s_and_saveexec_b64 s[34:35], s[30:31]
	s_xor_b64 s[30:31], exec, s[34:35]
	s_cbranch_execz .LBB0_257
	v_lshlrev_b32_e32 v25, 2, v125
	v_lshlrev_b64 v[26:27], v25, 1
	v_lshl_add_u64 v[22:23], v[26:27], 0, v[22:23]
	v_bfe_u32 v30, v22, 12, 4
	v_lshl_add_u32 v62, v30, 2, v117
	ds_read_b32 v70, v62 offset:8704
	v_and_b32_e32 v25, 15, v22
	v_bfe_u32 v26, v22, 4, 4
	v_bfe_u32 v27, v22, 8, 4
	v_bfe_u32 v37, v22, 16, 4
	v_bfe_u32 v41, v22, 20, 4
	v_bfe_u32 v46, v22, 24, 4
	v_lshrrev_b32_e32 v50, 28, v22
	v_and_b32_e32 v54, 15, v23
	v_bfe_u32 v58, v23, 4, 4
	v_bfe_u32 v62, v23, 8, 4
	v_bfe_u32 v107, v23, 12, 4
	v_bfe_u32 v111, v23, 16, 4
	v_lshrrev_b32_e32 v121, 20, v23
	s_waitcnt lgkmcnt(0)
	v_add_f32_e32 v124, v15, v70

; template <int MASK>
; __global__ void __launch_bounds__(256, 2) fwd_megakernel_t(Params p) {
;     ...
;           for (int k = 0; k < 16; k++) {
;             float bv = -3e38f;
;             int bi = 0, bj = 0;
; #pragma unroll
;             for (int i = 0; i <= k; i++) {
;               const int j = (int)((P >> (4 * i)) & 15ull);
;               const float cnd = sv0[i] + l1v[j];
;               if (!((E >> i) & 1u) && cnd > bv) { bv = cnd; bi = i; bj = j; }
;             }
;             best[k] = bv;
;             pidx[ob + k] = li[row * 17 + bi] * 128 + li[(128 + row) * 17 + bj];
;             if (bj == 15) E |= 1u << bi; else P += 1ull << (4 * bi);
.LBB0_259:
	s_or_b64 exec, exec, s[30:31]
	v_lshl_add_u32 v70, v25, 2, v117
	ds_read_b32 v70, v70 offset:8704
	v_lshl_add_u32 v72, v26, 2, v117
	ds_read_b32 v72, v72 offset:8704
	v_lshl_add_u32 v73, v27, 2, v117
	v_cmp_eq_u32_e64 s[30:31], 0, v33
	s_waitcnt lgkmcnt(1)
	v_add_f32_e32 v70, v16, v70
	v_cmp_lt_f32_e64 s[34:35], s43, v70
	ds_read_b32 v73, v73 offset:8704
	s_and_b64 s[30:31], s[30:31], s[34:35]
	v_cndmask_b32_e64 v70, v178, v70, s[30:31]
	s_waitcnt lgkmcnt(1)
	v_add_f32_e32 v72, v17, v72
	v_cndmask_b32_e64 v71, 0, v25, s[30:31]
	v_cmp_eq_u32_e64 s[30:31], 0, v34
	v_cmp_gt_f32_e64 s[34:35], v72, v70
	s_and_b64 s[30:31], s[30:31], s[34:35]
	v_cndmask_b32_e64 v70, v70, v72, s[30:31]
	s_waitcnt lgkmcnt(0)
	v_add_f32_e32 v73, v14, v73
	v_cndmask_b32_e64 v72, 0, 1, s[30:31]
	v_cndmask_b32_e64 v71, v71, v26, s[30:31]
	v_cmp_eq_u32_e64 s[30:31], 0, v36
	v_cmp_gt_f32_e64 s[34:35], v73, v70
	s_and_b64 s[30:31], s[30:31], s[34:35]
	v_cndmask_b32_e64 v70, v70, v73, s[30:31]
	v_lshl_add_u32 v73, v37, 2, v117
	ds_read_b32 v73, v73 offset:8704
	v_cndmask_b32_e64 v72, v72, 2, s[30:31]
	v_cndmask_b32_e64 v71, v71, v27, s[30:31]
	v_cmp_eq_u32_e64 s[30:31], 0, v35
	v_cmp_gt_f32_e64 s[34:35], v124, v70
	s_and_b64 s[30:31], s[30:31], s[34:35]
	v_cndmask_b32_e64 v70, v70, v124, s[30:31]
	s_waitcnt lgkmcnt(0)
	v_add_f32_e32 v73, v12, v73
	v_cndmask_b32_e64 v72, v72, 3, s[30:31]
	v_cndmask_b32_e64 v71, v71, v30, s[30:31]
	v_cmp_eq_u32_e64 s[30:31], 0, v40
	v_cmp_gt_f32_e64 s[34:35], v73, v70
	s_and_b64 s[30:31], s[30:31], s[34:35]
	v_cndmask_b32_e64 v70, v70, v73, s[30:31]
	v_lshl_add_u32 v73, v41, 2, v117
	ds_read_b32 v73, v73 offset:8704
	v_cndmask_b32_e64 v72, v72, 4, s[30:31]
	v_cndmask_b32_e64 v71, v71, v37, s[30:31]
	v_cmp_eq_u32_e64 s[30:31], 0, v44
	s_waitcnt lgkmcnt(0)
	v_add_f32_e32 v73, v13, v73
	v_cmp_gt_f32_e64 s[34:35], v73, v70
	s_and_b64 s[30:31], s[30:31], s[34:35]
	v_cndmask_b32_e64 v70, v70, v73, s[30:31]
	v_lshl_add_u32 v73, v46, 2, v117
	ds_read_b32 v73, v73 offset:8704
	v_cndmask_b32_e64 v72, v72, 5, s[30:31]
	v_cndmask_b32_e64 v71, v71, v41, s[30:31]
	v_cmp_eq_u32_e64 s[30:31], 0, v49
	s_waitcnt lgkmcnt(0)
	v_add_f32_e32 v124, v20, v73
	v_lshl_add_u32 v73, v50, 2, v117
	ds_read_b32 v73, v73 offset:8704
	v_cmp_gt_f32_e64 s[34:35], v124, v70
	s_and_b64 s[30:31], s[30:31], s[34:35]
	v_cndmask_b32_e64 v70, v70, v124, s[30:31]
	v_cndmask_b32_e64 v72, v72, 6, s[30:31]
	s_waitcnt lgkmcnt(0)
	v_add_f32_e32 v125, v21, v73
	v_lshl_add_u32 v73, v54, 2, v117
	ds_read_b32 v73, v73 offset:8704
	v_cndmask_b32_e64 v71, v71, v46, s[30:31]
	v_cmp_eq_u32_e64 s[30:31], 0, v53
	v_cmp_gt_f32_e64 s[34:35], v125, v70
	s_and_b64 s[30:31], s[30:31], s[34:35]
	v_cndmask_b32_e64 v70, v70, v125, s[30:31]
	s_waitcnt lgkmcnt(0)
	v_add_f32_e32 v73, v10, v73
	v_cndmask_b32_e64 v72, v72, 7, s[30:31]
	v_cndmask_b32_e64 v71, v71, v50, s[30:31]
	v_cmp_eq_u32_e64 s[30:31], 0, v57
	v_cmp_gt_f32_e64 s[34:35], v73, v70
	s_and_b64 s[30:31], s[30:31], s[34:35]
	v_cndmask_b32_e64 v70, v70, v73, s[30:31]
	v_lshl_add_u32 v73, v58, 2, v117
	ds_read_b32 v73, v73 offset:8704
	v_cndmask_b32_e64 v72, v72, 8, s[30:31]
	v_cndmask_b32_e64 v71, v71, v54, s[30:31]
	v_cmp_eq_u32_e64 s[30:31], 0, v59
	s_waitcnt lgkmcnt(0)
	v_add_f32_e32 v73, v11, v73
	v_cmp_gt_f32_e64 s[34:35], v73, v70
	s_and_b64 s[30:31], s[30:31], s[34:35]
	v_cndmask_b32_e64 v70, v70, v73, s[30:31]
	v_lshl_add_u32 v73, v62, 2, v117
	ds_read_b32 v73, v73 offset:8704
	v_cndmask_b32_e64 v72, v72, 9, s[30:31]
	v_cndmask_b32_e64 v71, v71, v58, s[30:31]
	v_cmp_eq_u32_e64 s[30:31], 0, v105
	s_waitcnt lgkmcnt(0)
	v_add_f32_e32 v73, v8, v73
	v_cmp_gt_f32_e64 s[34:35], v73, v70
	s_and_b64 s[30:31], s[30:31], s[34:35]
	v_cndmask_b32_e64 v70, v70, v73, s[30:31]
	v_lshl_add_u32 v73, v107, 2, v117
	ds_read_b32 v73, v73 offset:8704
	v_cndmask_b32_e64 v72, v72, 10, s[30:31]
	v_cndmask_b32_e64 v71, v71, v62, s[30:31]
	v_cmp_eq_u32_e64 s[30:31], 0, v109
	s_waitcnt lgkmcnt(0)
	v_add_f32_e32 v73, v9, v73
	v_cmp_gt_f32_e64 s[34:35], v73, v70
	s_and_b64 s[30:31], s[30:31], s[34:35]
	v_cndmask_b32_e64 v70, v70, v73, s[30:31]
	v_lshl_add_u32 v73, v111, 2, v117
	ds_read_b32 v73, v73 offset:8704
	v_cndmask_b32_e64 v72, v72, 11, s[30:31]
	v_cndmask_b32_e64 v71, v71, v107, s[30:31]
	v_cmp_eq_u32_e64 s[30:31], 0, v119
	s_waitcnt lgkmcnt(0)
	v_add_f32_e32 v73, v6, v73
	v_cmp_gt_f32_e64 s[34:35], v73, v70
	s_and_b64 s[30:31], s[30:31], s[34:35]
	v_cndmask_b32_e64 v70, v70, v73, s[30:31]
	v_lshl_add_u32 v73, v121, 2, v117
	ds_read_b32 v73, v73 offset:8704
	v_cndmask_b32_e64 v72, v72, 12, s[30:31]
	v_cndmask_b32_e64 v71, v71, v111, s[30:31]
	v_cmp_eq_u32_e64 s[30:31], 0, v122
	s_waitcnt lgkmcnt(0)
	v_add_f32_e32 v73, v7, v73
	v_cmp_gt_f32_e64 s[34:35], v73, v70
	s_and_b64 s[30:31], s[30:31], s[34:35]
	v_cndmask_b32_e64 v126, v70, v73, s[30:31]
	ds_read_b32 v70, v117 offset:8704
	v_cndmask_b32_e64 v127, v72, 13, s[30:31]
	v_cndmask_b32_e64 v128, v71, v121, s[30:31]
	s_waitcnt lgkmcnt(0)
	v_add_f32_e32 v129, v4, v70
	v_cmp_gt_f32_e64 s[30:31], v129, v126
	s_nop 1
	v_cndmask_b32_e64 v130, v127, 14, s[30:31]
	v_cndmask_b32_e64 v70, v128, 0, s[30:31]
	v_lshl_add_u32 v71, v130, 2, v117
	v_lshl_add_u32 v72, v70, 2, v117
	ds_read_b32 v71, v71 offset:17408
	ds_read_b32 v72, v72 offset:26112
	v_cmp_ne_u32_e64 s[34:35], 15, v70
	s_waitcnt lgkmcnt(0)
	v_lshl_add_u32 v71, v71, 7, v72
	v_mov_b32_e32 v230, v71
	s_and_saveexec_b64 s[72:73], s[34:35]
	s_xor_b64 s[34:35], exec, s[72:73]
	s_cbranch_execz .LBB0_261
	v_lshlrev_b32_e32 v25, 2, v130
	v_lshlrev_b64 v[26:27], v25, 1
	v_lshl_add_u64 v[22:23], v[26:27], 0, v[22:23]
	v_bfe_u32 v46, v22, 24, 4
	v_and_b32_e32 v25, 15, v22
	v_bfe_u32 v26, v22, 4, 4
	v_bfe_u32 v27, v22, 8, 4
	v_bfe_u32 v30, v22, 12, 4
	v_bfe_u32 v37, v22, 16, 4
	v_bfe_u32 v41, v22, 20, 4
	v_lshrrev_b32_e32 v50, 28, v22
	v_lshl_add_u32 v22, v46, 2, v117
	ds_read_b32 v22, v22 offset:8704
	v_and_b32_e32 v54, 15, v23
	v_bfe_u32 v58, v23, 4, 4
	v_bfe_u32 v62, v23, 8, 4
	v_bfe_u32 v107, v23, 12, 4
	s_waitcnt lgkmcnt(0)
	v_add_f32_e32 v124, v20, v22
	v_lshl_add_u32 v20, v50, 2, v117
	ds_read_b32 v20, v20 offset:8704
	v_bfe_u32 v111, v23, 16, 4
	v_bfe_u32 v121, v23, 20, 4
	v_lshrrev_b32_e32 v127, 24, v23
	s_waitcnt lgkmcnt(0)
	v_add_f32_e32 v125, v21, v20
